# ffn-up epilogue body hand-written with packed fp32 ops (same per-element arithmetic), sliding 3-row window, write-through stores
# speedup vs baseline: 1.0150x; 1.0086x over previous
.LBB0_920:
	v_lshl_or_b32 v134, v172, 2, s40
	v_mad_u64_u32 v[146:147], s[6:7], v1, s47, v[134:135]
	v_cvt_pk_bf16_f32 v106, v106, v107
	v_cvt_pk_bf16_f32 v107, v108, v109
	v_cvt_pk_bf16_f32 v98, v98, v99
	v_cvt_pk_bf16_f32 v99, v100, v101
	v_cvt_pk_bf16_f32 v74, v74, v75
	s_nop 0
	v_lshl_add_u32 v1, v146, 1, 0
	v_add_u32_e32 v108, 0x4000, v1
	v_add_u32_e32 v100, 0x6000, v1
	v_cvt_pk_bf16_f32 v66, v66, v67
	v_cvt_pk_bf16_f32 v58, v58, v59
	v_cvt_pk_bf16_f32 v59, v60, v61
	v_add_u32_e32 v60, 0x10820, v1
	v_cvt_pk_bf16_f32 v50, v50, v51
	v_cvt_pk_bf16_f32 v51, v52, v53
	v_add_u32_e32 v52, 0x12920, v1
	v_cvt_pk_bf16_f32 v42, v42, v43
	v_cvt_pk_bf16_f32 v43, v44, v45
	v_add_u32_e32 v44, 0x14a20, v1
	v_cvt_pk_bf16_f32 v34, v34, v35
	v_cvt_pk_bf16_f32 v35, v36, v37
	v_add_u32_e32 v36, 0x16b20, v1
	v_cvt_pk_bf16_f32 v26, v26, v27
	v_cvt_pk_bf16_f32 v27, v28, v29
	v_add_u32_e32 v28, 0x10920, v1
	v_cvt_pk_bf16_f32 v18, v18, v19
	v_cvt_pk_bf16_f32 v19, v20, v21
	v_add_u32_e32 v20, 0x12a20, v1
	v_cvt_pk_bf16_f32 v10, v10, v11
	v_cvt_pk_bf16_f32 v11, v12, v13
	v_add_u32_e32 v12, 0x14b20, v1
	v_cvt_pk_bf16_f32 v126, v126, v127
	v_cvt_pk_bf16_f32 v127, v128, v129
	v_cvt_pk_bf16_f32 v122, v122, v123
	v_cvt_pk_bf16_f32 v123, v124, v125
	ds_write2_b64 v1, v[126:127], v[122:123] offset1:4
	v_cvt_pk_bf16_f32 v114, v114, v115
	v_cvt_pk_bf16_f32 v115, v116, v117
	v_add_u32_e32 v116, 0x2000, v1
	v_cvt_pk_bf16_f32 v94, v94, v95
	v_cvt_pk_bf16_f32 v95, v96, v97
	v_cvt_pk_bf16_f32 v90, v90, v91
	v_cvt_pk_bf16_f32 v91, v92, v93
	ds_write2_b64 v1, v[94:95], v[90:91] offset0:32 offset1:36
	v_cvt_pk_bf16_f32 v78, v78, v79
	v_cvt_pk_bf16_f32 v79, v80, v81
	v_cvt_pk_bf16_f32 v75, v76, v77
	ds_write2_b64 v108, v[78:79], v[74:75] offset0:96 offset1:100
	v_cvt_pk_bf16_f32 v70, v70, v71
	v_cvt_pk_bf16_f32 v71, v72, v73
	v_cvt_pk_bf16_f32 v67, v68, v69
	ds_write2_b64 v100, v[70:71], v[66:67] offset0:128 offset1:132
	v_add_u32_e32 v66, 0x10800, v1
	ds_write_b64 v60, v[58:59]
	v_add_u32_e32 v58, 0x12900, v1
	ds_write_b64 v52, v[50:51]
	v_add_u32_e32 v50, 0x14a00, v1
	ds_write_b64 v44, v[42:43]
	v_add_u32_e32 v42, 0x16b00, v1
	ds_write_b64 v36, v[34:35]
	v_add_u32_e32 v34, 0x10900, v1
	ds_write_b64 v28, v[26:27]
	v_add_u32_e32 v26, 0x12a00, v1
	ds_write_b64 v20, v[18:19]
	v_add_u32_e32 v18, 0x14b00, v1
	ds_write_b64 v12, v[10:11]
	v_add_u32_e32 v10, 0x16c00, v1
	v_cvt_pk_bf16_f32 v2, v2, v3
	v_add_u32_e32 v1, 0x16c20, v1
	v_mov_b32_e32 v74, v0
	v_cvt_pk_bf16_f32 v118, v118, v119
	v_cvt_pk_bf16_f32 v119, v120, v121
	ds_write2_b64 v116, v[118:119], v[114:115] offset0:32 offset1:36
	v_cvt_pk_bf16_f32 v110, v110, v111
	v_cvt_pk_bf16_f32 v111, v112, v113
	ds_write2_b64 v108, v[110:111], v[106:107] offset0:64 offset1:68
	v_cvt_pk_bf16_f32 v102, v102, v103
	v_cvt_pk_bf16_f32 v103, v104, v105
	ds_write2_b64 v100, v[102:103], v[98:99] offset0:96 offset1:100
	v_cvt_pk_bf16_f32 v86, v86, v87
	v_cvt_pk_bf16_f32 v87, v88, v89
	v_cvt_pk_bf16_f32 v82, v82, v83
	v_cvt_pk_bf16_f32 v83, v84, v85
	ds_write2_b64 v116, v[86:87], v[82:83] offset0:64 offset1:68
	v_cvt_pk_bf16_f32 v62, v62, v63
	v_cvt_pk_bf16_f32 v63, v64, v65
	ds_write_b64 v66, v[62:63]
	v_cvt_pk_bf16_f32 v54, v54, v55
	v_cvt_pk_bf16_f32 v55, v56, v57
	ds_write_b64 v58, v[54:55]
	v_cvt_pk_bf16_f32 v46, v46, v47
	v_cvt_pk_bf16_f32 v47, v48, v49
	ds_write_b64 v50, v[46:47]
	v_cvt_pk_bf16_f32 v38, v38, v39
	v_cvt_pk_bf16_f32 v39, v40, v41
	ds_write_b64 v42, v[38:39]
	v_cvt_pk_bf16_f32 v30, v30, v31
	v_cvt_pk_bf16_f32 v31, v32, v33
	ds_write_b64 v34, v[30:31]
	v_cvt_pk_bf16_f32 v22, v22, v23
	v_cvt_pk_bf16_f32 v23, v24, v25
	ds_write_b64 v26, v[22:23]
	v_cvt_pk_bf16_f32 v14, v14, v15
	v_cvt_pk_bf16_f32 v15, v16, v17
	ds_write_b64 v18, v[14:15]
	v_cvt_pk_bf16_f32 v6, v6, v7
	v_cvt_pk_bf16_f32 v7, v8, v9
	ds_write_b64 v10, v[6:7]
	v_cvt_pk_bf16_f32 v3, v4, v5
	ds_write_b64 v1, v[2:3]
	s_waitcnt lgkmcnt(0)
	s_barrier
	v_and_b32_e32 v225, 15, v0
	v_lshrrev_b32_e32 v224, 4, v0
	v_lshrrev_b32_e32 v222, 3, v225
	v_and_b32_e32 v225, 7, v225
	v_lshlrev_b32_e32 v225, 3, v225
	s_lshl_b32 s34, s5, 7
	v_lshl_or_b32 v216, v222, 6, v225
	v_or_b32_e32 v216, s34, v216
	v_lshl_or_b32 v222, v222, 7, v225
	v_lshlrev_b32_e32 v222, 1, v222
	v_mul_u32_u24_e32 v225, 0x1080, v224
	v_add_u32_e32 v222, v222, v225
	s_lshl_b32 s34, s35, 8
	v_lshl_add_u32 v223, v224, 3, s34
	v_mul_u32_u24_e32 v223, 0x1600, v223
	v_lshl_add_u32 v223, v216, 1, v223
	v_lshlrev_b32_e32 v216, 2, v216
	v_add_u32_e32 v217, 0x5800, v216
	v_add_u32_e32 v218, 0xb000, v216
	v_add_u32_e32 v219, 0x2c00, v216
	v_add_u32_e32 v220, 0x8400, v216
	v_add_u32_e32 v221, 0xdc00, v216
	global_load_dwordx4 v[66:69], v216, s[12:13]
	global_load_dwordx4 v[70:73], v216, s[12:13] offset:16
	global_load_dwordx4 v[74:77], v217, s[12:13]
	global_load_dwordx4 v[78:81], v217, s[12:13] offset:16
	global_load_dwordx4 v[82:85], v218, s[12:13]
	global_load_dwordx4 v[86:89], v218, s[12:13] offset:16
	global_load_dwordx4 v[98:101], v219, s[12:13]
	global_load_dwordx4 v[102:105], v219, s[12:13] offset:16
	global_load_dwordx4 v[106:109], v220, s[12:13]
	global_load_dwordx4 v[110:113], v220, s[12:13] offset:16
	global_load_dwordx4 v[114:117], v221, s[12:13]
	global_load_dwordx4 v[118:121], v221, s[12:13] offset:16
	global_load_dwordx4 v[90:93], v216, s[14:15]
	global_load_dwordx4 v[94:97], v216, s[14:15] offset:16
	global_load_dwordx4 v[122:125], v219, s[14:15]
	global_load_dwordx4 v[126:129], v219, s[14:15] offset:16
	v_mov_b32_e32 v214, 0xbfb8aa3b
	v_mov_b32_e32 v215, 0xbfb8aa3b
	v_cmp_ne_u32_e32 vcc, 0, v224
	s_nop 1
	s_and_saveexec_b64 s[38:39], vcc
	v_add_u32_e32 v225, 0xfffffdf0, v222
	ds_read_b128 v[204:207], v225
	ds_read_b128 v[210:213], v225 offset:128
	s_or_b64 exec, exec, s[38:39]
	s_waitcnt lgkmcnt(0)
	v_lshlrev_b32_e32 v2, 16, v204
	v_and_b32_e32 v3, 0xffff0000, v204
	v_lshlrev_b32_e32 v4, 16, v205
	v_and_b32_e32 v5, 0xffff0000, v205
	v_lshlrev_b32_e32 v6, 16, v206
	v_and_b32_e32 v7, 0xffff0000, v206
	v_lshlrev_b32_e32 v8, 16, v207
	v_and_b32_e32 v9, 0xffff0000, v207
	v_lshlrev_b32_e32 v10, 16, v210
	v_and_b32_e32 v11, 0xffff0000, v210
	v_lshlrev_b32_e32 v12, 16, v211
	v_and_b32_e32 v13, 0xffff0000, v211
	v_lshlrev_b32_e32 v14, 16, v212
	v_and_b32_e32 v15, 0xffff0000, v212
	v_lshlrev_b32_e32 v16, 16, v213
	v_and_b32_e32 v17, 0xffff0000, v213
	v_cmp_eq_u32_e32 vcc, 0, v224
	s_nop 1
	v_cndmask_b32_e64 v2, v2, 0, vcc
	v_cndmask_b32_e64 v3, v3, 0, vcc
	v_cndmask_b32_e64 v4, v4, 0, vcc
	v_cndmask_b32_e64 v5, v5, 0, vcc
	v_cndmask_b32_e64 v6, v6, 0, vcc
	v_cndmask_b32_e64 v7, v7, 0, vcc
	v_cndmask_b32_e64 v8, v8, 0, vcc
	v_cndmask_b32_e64 v9, v9, 0, vcc
	v_cndmask_b32_e64 v10, v10, 0, vcc
	v_cndmask_b32_e64 v11, v11, 0, vcc
	v_cndmask_b32_e64 v12, v12, 0, vcc
	v_cndmask_b32_e64 v13, v13, 0, vcc
	v_cndmask_b32_e64 v14, v14, 0, vcc
	v_cndmask_b32_e64 v15, v15, 0, vcc
	v_cndmask_b32_e64 v16, v16, 0, vcc
	v_cndmask_b32_e64 v17, v17, 0, vcc
	ds_read_b128 v[204:207], v222
	ds_read_b128 v[210:213], v222 offset:128
	s_waitcnt lgkmcnt(0)
	v_lshlrev_b32_e32 v18, 16, v204
	v_and_b32_e32 v19, 0xffff0000, v204
	v_lshlrev_b32_e32 v20, 16, v205
	v_and_b32_e32 v21, 0xffff0000, v205
	v_lshlrev_b32_e32 v22, 16, v206
	v_and_b32_e32 v23, 0xffff0000, v206
	v_lshlrev_b32_e32 v24, 16, v207
	v_and_b32_e32 v25, 0xffff0000, v207
	v_lshlrev_b32_e32 v26, 16, v210
	v_and_b32_e32 v27, 0xffff0000, v210
	v_lshlrev_b32_e32 v28, 16, v211
	v_and_b32_e32 v29, 0xffff0000, v211
	v_lshlrev_b32_e32 v30, 16, v212
	v_and_b32_e32 v31, 0xffff0000, v212
	v_lshlrev_b32_e32 v32, 16, v213
	v_and_b32_e32 v33, 0xffff0000, v213
	ds_read_b128 v[204:207], v222 offset:528
	ds_read_b128 v[210:213], v222 offset:656
	s_waitcnt lgkmcnt(0)
	v_lshlrev_b32_e32 v34, 16, v204
	v_and_b32_e32 v35, 0xffff0000, v204
	v_lshlrev_b32_e32 v36, 16, v205
	v_and_b32_e32 v37, 0xffff0000, v205
	v_lshlrev_b32_e32 v38, 16, v206
	v_and_b32_e32 v39, 0xffff0000, v206
	v_lshlrev_b32_e32 v40, 16, v207
	v_and_b32_e32 v41, 0xffff0000, v207
	v_lshlrev_b32_e32 v42, 16, v210
	v_and_b32_e32 v43, 0xffff0000, v210
	v_lshlrev_b32_e32 v44, 16, v211
	v_and_b32_e32 v45, 0xffff0000, v211
	v_lshlrev_b32_e32 v46, 16, v212
	v_and_b32_e32 v47, 0xffff0000, v212
	v_lshlrev_b32_e32 v48, 16, v213
	v_and_b32_e32 v49, 0xffff0000, v213
	ds_read_b128 v[204:207], v222 offset:1056
	ds_read_b128 v[210:213], v222 offset:1184
	s_waitcnt vmcnt(0)
	v_pk_fma_f32 v[176:177], v[66:67], v[2:3], v[90:91]
	v_pk_fma_f32 v[178:179], v[68:69], v[4:5], v[92:93]
	v_pk_fma_f32 v[180:181], v[70:71], v[6:7], v[94:95]
	v_pk_fma_f32 v[182:183], v[72:73], v[8:9], v[96:97]
	v_pk_fma_f32 v[184:185], v[98:99], v[10:11], v[122:123]
	v_pk_fma_f32 v[186:187], v[100:101], v[12:13], v[124:125]
	v_pk_fma_f32 v[188:189], v[102:103], v[14:15], v[126:127]
	v_pk_fma_f32 v[190:191], v[104:105], v[16:17], v[128:129]
	v_pk_fma_f32 v[176:177], v[74:75], v[18:19], v[176:177]
	v_pk_fma_f32 v[178:179], v[76:77], v[20:21], v[178:179]
	v_pk_fma_f32 v[180:181], v[78:79], v[22:23], v[180:181]
	v_pk_fma_f32 v[182:183], v[80:81], v[24:25], v[182:183]
	v_pk_fma_f32 v[184:185], v[106:107], v[26:27], v[184:185]
	v_pk_fma_f32 v[186:187], v[108:109], v[28:29], v[186:187]
	v_pk_fma_f32 v[188:189], v[110:111], v[30:31], v[188:189]
	v_pk_fma_f32 v[190:191], v[112:113], v[32:33], v[190:191]
	v_pk_fma_f32 v[176:177], v[82:83], v[34:35], v[176:177]
	v_pk_fma_f32 v[178:179], v[84:85], v[36:37], v[178:179]
	v_pk_fma_f32 v[180:181], v[86:87], v[38:39], v[180:181]
	v_pk_fma_f32 v[182:183], v[88:89], v[40:41], v[182:183]
	v_pk_fma_f32 v[184:185], v[114:115], v[42:43], v[184:185]
	v_pk_fma_f32 v[186:187], v[116:117], v[44:45], v[186:187]
	v_pk_fma_f32 v[188:189], v[118:119], v[46:47], v[188:189]
	v_pk_fma_f32 v[190:191], v[120:121], v[48:49], v[190:191]
	v_pk_mul_f32 v[192:193], v[176:177], v[214:215]
	v_pk_mul_f32 v[194:195], v[178:179], v[214:215]
	v_pk_mul_f32 v[196:197], v[180:181], v[214:215]
	v_pk_mul_f32 v[198:199], v[182:183], v[214:215]
	v_exp_f32_e32 v192, v192
	v_exp_f32_e32 v193, v193
	v_exp_f32_e32 v194, v194
	v_exp_f32_e32 v195, v195
	v_exp_f32_e32 v196, v196
	v_exp_f32_e32 v197, v197
	v_exp_f32_e32 v198, v198
	v_exp_f32_e32 v199, v199
	v_pk_add_f32 v[192:193], v[192:193], 1.0 op_sel_hi:[1,0]
	v_pk_add_f32 v[194:195], v[194:195], 1.0 op_sel_hi:[1,0]
	v_pk_add_f32 v[196:197], v[196:197], 1.0 op_sel_hi:[1,0]
	v_pk_add_f32 v[198:199], v[198:199], 1.0 op_sel_hi:[1,0]
	v_rcp_f32_e32 v192, v192
	v_rcp_f32_e32 v193, v193
	v_rcp_f32_e32 v194, v194
	v_rcp_f32_e32 v195, v195
	v_rcp_f32_e32 v196, v196
	v_rcp_f32_e32 v197, v197
	v_rcp_f32_e32 v198, v198
	v_rcp_f32_e32 v199, v199
	s_waitcnt lgkmcnt(0)
	v_lshlrev_b32_e32 v50, 16, v204
	v_and_b32_e32 v51, 0xffff0000, v204
	v_lshlrev_b32_e32 v52, 16, v205
	v_and_b32_e32 v53, 0xffff0000, v205
	v_lshlrev_b32_e32 v54, 16, v206
	v_and_b32_e32 v55, 0xffff0000, v206
	v_lshlrev_b32_e32 v56, 16, v207
	v_and_b32_e32 v57, 0xffff0000, v207
	v_lshlrev_b32_e32 v58, 16, v210
	v_and_b32_e32 v59, 0xffff0000, v210
	v_lshlrev_b32_e32 v60, 16, v211
	v_and_b32_e32 v61, 0xffff0000, v211
	v_lshlrev_b32_e32 v62, 16, v212
	v_and_b32_e32 v63, 0xffff0000, v212
	v_lshlrev_b32_e32 v64, 16, v213
	v_and_b32_e32 v65, 0xffff0000, v213
	ds_read_b128 v[204:207], v222 offset:1584
	ds_read_b128 v[210:213], v222 offset:1712
	v_pk_mul_f32 v[176:177], v[176:177], v[192:193]
	v_pk_mul_f32 v[178:179], v[178:179], v[194:195]
	v_pk_mul_f32 v[180:181], v[180:181], v[196:197]
	v_pk_mul_f32 v[182:183], v[182:183], v[198:199]
	v_pk_mul_f32 v[176:177], v[176:177], v[184:185]
	v_pk_mul_f32 v[178:179], v[178:179], v[186:187]
	v_pk_mul_f32 v[180:181], v[180:181], v[188:189]
	v_pk_mul_f32 v[182:183], v[182:183], v[190:191]
	v_cvt_pk_bf16_f32 v200, v176, v177
	v_cvt_pk_bf16_f32 v201, v178, v179
	v_cvt_pk_bf16_f32 v202, v180, v181
	v_cvt_pk_bf16_f32 v203, v182, v183
	s_and_b32 s36, s35, 3
	s_cmp_eq_u32 s36, 0
	s_cselect_b64 s[38:39], -1, 0
	s_cmp_lt_i32 s35, 32
	s_cselect_b64 vcc, -1, 0
	s_or_b64 s[38:39], s[38:39], vcc
	v_cmp_ne_u32_e32 vcc, 0, v224
	s_nop 1
	s_or_b64 vcc, vcc, s[38:39]
	s_and_saveexec_b64 s[38:39], vcc
	global_store_dwordx4 v223, v[200:203], s[0:1] sc1
	s_or_b64 exec, exec, s[38:39]
	v_add_u32_e32 v223, 0x1600, v223
	v_pk_fma_f32 v[176:177], v[66:67], v[18:19], v[90:91]
	v_pk_fma_f32 v[178:179], v[68:69], v[20:21], v[92:93]
	v_pk_fma_f32 v[180:181], v[70:71], v[22:23], v[94:95]
	v_pk_fma_f32 v[182:183], v[72:73], v[24:25], v[96:97]
	v_pk_fma_f32 v[184:185], v[98:99], v[26:27], v[122:123]
	v_pk_fma_f32 v[186:187], v[100:101], v[28:29], v[124:125]
	v_pk_fma_f32 v[188:189], v[102:103], v[30:31], v[126:127]
	v_pk_fma_f32 v[190:191], v[104:105], v[32:33], v[128:129]
	v_pk_fma_f32 v[176:177], v[74:75], v[34:35], v[176:177]
	v_pk_fma_f32 v[178:179], v[76:77], v[36:37], v[178:179]
	v_pk_fma_f32 v[180:181], v[78:79], v[38:39], v[180:181]
	v_pk_fma_f32 v[182:183], v[80:81], v[40:41], v[182:183]
	v_pk_fma_f32 v[184:185], v[106:107], v[42:43], v[184:185]
	v_pk_fma_f32 v[186:187], v[108:109], v[44:45], v[186:187]
	v_pk_fma_f32 v[188:189], v[110:111], v[46:47], v[188:189]
	v_pk_fma_f32 v[190:191], v[112:113], v[48:49], v[190:191]
	v_pk_fma_f32 v[176:177], v[82:83], v[50:51], v[176:177]
	v_pk_fma_f32 v[178:179], v[84:85], v[52:53], v[178:179]
	v_pk_fma_f32 v[180:181], v[86:87], v[54:55], v[180:181]
	v_pk_fma_f32 v[182:183], v[88:89], v[56:57], v[182:183]
	v_pk_fma_f32 v[184:185], v[114:115], v[58:59], v[184:185]
	v_pk_fma_f32 v[186:187], v[116:117], v[60:61], v[186:187]
	v_pk_fma_f32 v[188:189], v[118:119], v[62:63], v[188:189]
	v_pk_fma_f32 v[190:191], v[120:121], v[64:65], v[190:191]
	v_pk_mul_f32 v[192:193], v[176:177], v[214:215]
	v_pk_mul_f32 v[194:195], v[178:179], v[214:215]
	v_pk_mul_f32 v[196:197], v[180:181], v[214:215]
	v_pk_mul_f32 v[198:199], v[182:183], v[214:215]
	v_exp_f32_e32 v192, v192
	v_exp_f32_e32 v193, v193
	v_exp_f32_e32 v194, v194
	v_exp_f32_e32 v195, v195
	v_exp_f32_e32 v196, v196
	v_exp_f32_e32 v197, v197
	v_exp_f32_e32 v198, v198
	v_exp_f32_e32 v199, v199
	v_pk_add_f32 v[192:193], v[192:193], 1.0 op_sel_hi:[1,0]
	v_pk_add_f32 v[194:195], v[194:195], 1.0 op_sel_hi:[1,0]
	v_pk_add_f32 v[196:197], v[196:197], 1.0 op_sel_hi:[1,0]
	v_pk_add_f32 v[198:199], v[198:199], 1.0 op_sel_hi:[1,0]
	v_rcp_f32_e32 v192, v192
	v_rcp_f32_e32 v193, v193
	v_rcp_f32_e32 v194, v194
	v_rcp_f32_e32 v195, v195
	v_rcp_f32_e32 v196, v196
	v_rcp_f32_e32 v197, v197
	v_rcp_f32_e32 v198, v198
	v_rcp_f32_e32 v199, v199
	s_waitcnt lgkmcnt(0)
	v_lshlrev_b32_e32 v2, 16, v204
	v_and_b32_e32 v3, 0xffff0000, v204
	v_lshlrev_b32_e32 v4, 16, v205
	v_and_b32_e32 v5, 0xffff0000, v205
	v_lshlrev_b32_e32 v6, 16, v206
	v_and_b32_e32 v7, 0xffff0000, v206
	v_lshlrev_b32_e32 v8, 16, v207
	v_and_b32_e32 v9, 0xffff0000, v207
	v_lshlrev_b32_e32 v10, 16, v210
	v_and_b32_e32 v11, 0xffff0000, v210
	v_lshlrev_b32_e32 v12, 16, v211
	v_and_b32_e32 v13, 0xffff0000, v211
	v_lshlrev_b32_e32 v14, 16, v212
	v_and_b32_e32 v15, 0xffff0000, v212
	v_lshlrev_b32_e32 v16, 16, v213
	v_and_b32_e32 v17, 0xffff0000, v213
	ds_read_b128 v[204:207], v222 offset:2112
	ds_read_b128 v[210:213], v222 offset:2240
	v_pk_mul_f32 v[176:177], v[176:177], v[192:193]
	v_pk_mul_f32 v[178:179], v[178:179], v[194:195]
	v_pk_mul_f32 v[180:181], v[180:181], v[196:197]
	v_pk_mul_f32 v[182:183], v[182:183], v[198:199]
	v_pk_mul_f32 v[176:177], v[176:177], v[184:185]
	v_pk_mul_f32 v[178:179], v[178:179], v[186:187]
	v_pk_mul_f32 v[180:181], v[180:181], v[188:189]
	v_pk_mul_f32 v[182:183], v[182:183], v[190:191]
	v_cvt_pk_bf16_f32 v200, v176, v177
	v_cvt_pk_bf16_f32 v201, v178, v179
	v_cvt_pk_bf16_f32 v202, v180, v181
	v_cvt_pk_bf16_f32 v203, v182, v183
	global_store_dwordx4 v223, v[200:203], s[0:1] sc1
	v_add_u32_e32 v223, 0x1600, v223
	v_pk_fma_f32 v[176:177], v[66:67], v[34:35], v[90:91]
	v_pk_fma_f32 v[178:179], v[68:69], v[36:37], v[92:93]
	v_pk_fma_f32 v[180:181], v[70:71], v[38:39], v[94:95]
	v_pk_fma_f32 v[182:183], v[72:73], v[40:41], v[96:97]
	v_pk_fma_f32 v[184:185], v[98:99], v[42:43], v[122:123]
	v_pk_fma_f32 v[186:187], v[100:101], v[44:45], v[124:125]
	v_pk_fma_f32 v[188:189], v[102:103], v[46:47], v[126:127]
	v_pk_fma_f32 v[190:191], v[104:105], v[48:49], v[128:129]
	v_pk_fma_f32 v[176:177], v[74:75], v[50:51], v[176:177]
	v_pk_fma_f32 v[178:179], v[76:77], v[52:53], v[178:179]
	v_pk_fma_f32 v[180:181], v[78:79], v[54:55], v[180:181]
	v_pk_fma_f32 v[182:183], v[80:81], v[56:57], v[182:183]
	v_pk_fma_f32 v[184:185], v[106:107], v[58:59], v[184:185]
	v_pk_fma_f32 v[186:187], v[108:109], v[60:61], v[186:187]
	v_pk_fma_f32 v[188:189], v[110:111], v[62:63], v[188:189]
	v_pk_fma_f32 v[190:191], v[112:113], v[64:65], v[190:191]
	v_pk_fma_f32 v[176:177], v[82:83], v[2:3], v[176:177]
	v_pk_fma_f32 v[178:179], v[84:85], v[4:5], v[178:179]
	v_pk_fma_f32 v[180:181], v[86:87], v[6:7], v[180:181]
	v_pk_fma_f32 v[182:183], v[88:89], v[8:9], v[182:183]
	v_pk_fma_f32 v[184:185], v[114:115], v[10:11], v[184:185]
	v_pk_fma_f32 v[186:187], v[116:117], v[12:13], v[186:187]
	v_pk_fma_f32 v[188:189], v[118:119], v[14:15], v[188:189]
	v_pk_fma_f32 v[190:191], v[120:121], v[16:17], v[190:191]
	v_pk_mul_f32 v[192:193], v[176:177], v[214:215]
	v_pk_mul_f32 v[194:195], v[178:179], v[214:215]
	v_pk_mul_f32 v[196:197], v[180:181], v[214:215]
	v_pk_mul_f32 v[198:199], v[182:183], v[214:215]
	v_exp_f32_e32 v192, v192
	v_exp_f32_e32 v193, v193
	v_exp_f32_e32 v194, v194
	v_exp_f32_e32 v195, v195
	v_exp_f32_e32 v196, v196
	v_exp_f32_e32 v197, v197
	v_exp_f32_e32 v198, v198
	v_exp_f32_e32 v199, v199
	v_pk_add_f32 v[192:193], v[192:193], 1.0 op_sel_hi:[1,0]
	v_pk_add_f32 v[194:195], v[194:195], 1.0 op_sel_hi:[1,0]
	v_pk_add_f32 v[196:197], v[196:197], 1.0 op_sel_hi:[1,0]
	v_pk_add_f32 v[198:199], v[198:199], 1.0 op_sel_hi:[1,0]
	v_rcp_f32_e32 v192, v192
	v_rcp_f32_e32 v193, v193
	v_rcp_f32_e32 v194, v194
	v_rcp_f32_e32 v195, v195
	v_rcp_f32_e32 v196, v196
	v_rcp_f32_e32 v197, v197
	v_rcp_f32_e32 v198, v198
	v_rcp_f32_e32 v199, v199
	s_waitcnt lgkmcnt(0)
	v_lshlrev_b32_e32 v18, 16, v204
	v_and_b32_e32 v19, 0xffff0000, v204
	v_lshlrev_b32_e32 v20, 16, v205
	v_and_b32_e32 v21, 0xffff0000, v205
	v_lshlrev_b32_e32 v22, 16, v206
	v_and_b32_e32 v23, 0xffff0000, v206
	v_lshlrev_b32_e32 v24, 16, v207
	v_and_b32_e32 v25, 0xffff0000, v207
	v_lshlrev_b32_e32 v26, 16, v210
	v_and_b32_e32 v27, 0xffff0000, v210
	v_lshlrev_b32_e32 v28, 16, v211
	v_and_b32_e32 v29, 0xffff0000, v211
	v_lshlrev_b32_e32 v30, 16, v212
	v_and_b32_e32 v31, 0xffff0000, v212
	v_lshlrev_b32_e32 v32, 16, v213
	v_and_b32_e32 v33, 0xffff0000, v213
	ds_read_b128 v[204:207], v222 offset:2640
	ds_read_b128 v[210:213], v222 offset:2768
	v_pk_mul_f32 v[176:177], v[176:177], v[192:193]
	v_pk_mul_f32 v[178:179], v[178:179], v[194:195]
	v_pk_mul_f32 v[180:181], v[180:181], v[196:197]
	v_pk_mul_f32 v[182:183], v[182:183], v[198:199]
	v_pk_mul_f32 v[176:177], v[176:177], v[184:185]
	v_pk_mul_f32 v[178:179], v[178:179], v[186:187]
	v_pk_mul_f32 v[180:181], v[180:181], v[188:189]
	v_pk_mul_f32 v[182:183], v[182:183], v[190:191]
	v_cvt_pk_bf16_f32 v200, v176, v177
	v_cvt_pk_bf16_f32 v201, v178, v179
	v_cvt_pk_bf16_f32 v202, v180, v181
	v_cvt_pk_bf16_f32 v203, v182, v183
	global_store_dwordx4 v223, v[200:203], s[0:1] sc1
	v_add_u32_e32 v223, 0x1600, v223
	v_pk_fma_f32 v[176:177], v[66:67], v[50:51], v[90:91]
	v_pk_fma_f32 v[178:179], v[68:69], v[52:53], v[92:93]
	v_pk_fma_f32 v[180:181], v[70:71], v[54:55], v[94:95]
	v_pk_fma_f32 v[182:183], v[72:73], v[56:57], v[96:97]
	v_pk_fma_f32 v[184:185], v[98:99], v[58:59], v[122:123]
	v_pk_fma_f32 v[186:187], v[100:101], v[60:61], v[124:125]
	v_pk_fma_f32 v[188:189], v[102:103], v[62:63], v[126:127]
	v_pk_fma_f32 v[190:191], v[104:105], v[64:65], v[128:129]
	v_pk_fma_f32 v[176:177], v[74:75], v[2:3], v[176:177]
	v_pk_fma_f32 v[178:179], v[76:77], v[4:5], v[178:179]
	v_pk_fma_f32 v[180:181], v[78:79], v[6:7], v[180:181]
	v_pk_fma_f32 v[182:183], v[80:81], v[8:9], v[182:183]
	v_pk_fma_f32 v[184:185], v[106:107], v[10:11], v[184:185]
	v_pk_fma_f32 v[186:187], v[108:109], v[12:13], v[186:187]
	v_pk_fma_f32 v[188:189], v[110:111], v[14:15], v[188:189]
	v_pk_fma_f32 v[190:191], v[112:113], v[16:17], v[190:191]
	v_pk_fma_f32 v[176:177], v[82:83], v[18:19], v[176:177]
	v_pk_fma_f32 v[178:179], v[84:85], v[20:21], v[178:179]
	v_pk_fma_f32 v[180:181], v[86:87], v[22:23], v[180:181]
	v_pk_fma_f32 v[182:183], v[88:89], v[24:25], v[182:183]
	v_pk_fma_f32 v[184:185], v[114:115], v[26:27], v[184:185]
	v_pk_fma_f32 v[186:187], v[116:117], v[28:29], v[186:187]
	v_pk_fma_f32 v[188:189], v[118:119], v[30:31], v[188:189]
	v_pk_fma_f32 v[190:191], v[120:121], v[32:33], v[190:191]
	v_pk_mul_f32 v[192:193], v[176:177], v[214:215]
	v_pk_mul_f32 v[194:195], v[178:179], v[214:215]
	v_pk_mul_f32 v[196:197], v[180:181], v[214:215]
	v_pk_mul_f32 v[198:199], v[182:183], v[214:215]
	v_exp_f32_e32 v192, v192
	v_exp_f32_e32 v193, v193
	v_exp_f32_e32 v194, v194
	v_exp_f32_e32 v195, v195
	v_exp_f32_e32 v196, v196
	v_exp_f32_e32 v197, v197
	v_exp_f32_e32 v198, v198
	v_exp_f32_e32 v199, v199
	v_pk_add_f32 v[192:193], v[192:193], 1.0 op_sel_hi:[1,0]
	v_pk_add_f32 v[194:195], v[194:195], 1.0 op_sel_hi:[1,0]
	v_pk_add_f32 v[196:197], v[196:197], 1.0 op_sel_hi:[1,0]
	v_pk_add_f32 v[198:199], v[198:199], 1.0 op_sel_hi:[1,0]
	v_rcp_f32_e32 v192, v192
	v_rcp_f32_e32 v193, v193
	v_rcp_f32_e32 v194, v194
	v_rcp_f32_e32 v195, v195
	v_rcp_f32_e32 v196, v196
	v_rcp_f32_e32 v197, v197
	v_rcp_f32_e32 v198, v198
	v_rcp_f32_e32 v199, v199
	s_waitcnt lgkmcnt(0)
	v_lshlrev_b32_e32 v34, 16, v204
	v_and_b32_e32 v35, 0xffff0000, v204
	v_lshlrev_b32_e32 v36, 16, v205
	v_and_b32_e32 v37, 0xffff0000, v205
	v_lshlrev_b32_e32 v38, 16, v206
	v_and_b32_e32 v39, 0xffff0000, v206
	v_lshlrev_b32_e32 v40, 16, v207
	v_and_b32_e32 v41, 0xffff0000, v207
	v_lshlrev_b32_e32 v42, 16, v210
	v_and_b32_e32 v43, 0xffff0000, v210
	v_lshlrev_b32_e32 v44, 16, v211
	v_and_b32_e32 v45, 0xffff0000, v211
	v_lshlrev_b32_e32 v46, 16, v212
	v_and_b32_e32 v47, 0xffff0000, v212
	v_lshlrev_b32_e32 v48, 16, v213
	v_and_b32_e32 v49, 0xffff0000, v213
	ds_read_b128 v[204:207], v222 offset:3168
	ds_read_b128 v[210:213], v222 offset:3296
	v_pk_mul_f32 v[176:177], v[176:177], v[192:193]
	v_pk_mul_f32 v[178:179], v[178:179], v[194:195]
	v_pk_mul_f32 v[180:181], v[180:181], v[196:197]
	v_pk_mul_f32 v[182:183], v[182:183], v[198:199]
	v_pk_mul_f32 v[176:177], v[176:177], v[184:185]
	v_pk_mul_f32 v[178:179], v[178:179], v[186:187]
	v_pk_mul_f32 v[180:181], v[180:181], v[188:189]
	v_pk_mul_f32 v[182:183], v[182:183], v[190:191]
	v_cvt_pk_bf16_f32 v200, v176, v177
	v_cvt_pk_bf16_f32 v201, v178, v179
	v_cvt_pk_bf16_f32 v202, v180, v181
	v_cvt_pk_bf16_f32 v203, v182, v183
	global_store_dwordx4 v223, v[200:203], s[0:1] sc1
	v_add_u32_e32 v223, 0x1600, v223
	v_pk_fma_f32 v[176:177], v[66:67], v[2:3], v[90:91]
	v_pk_fma_f32 v[178:179], v[68:69], v[4:5], v[92:93]
	v_pk_fma_f32 v[180:181], v[70:71], v[6:7], v[94:95]
	v_pk_fma_f32 v[182:183], v[72:73], v[8:9], v[96:97]
	v_pk_fma_f32 v[184:185], v[98:99], v[10:11], v[122:123]
	v_pk_fma_f32 v[186:187], v[100:101], v[12:13], v[124:125]
	v_pk_fma_f32 v[188:189], v[102:103], v[14:15], v[126:127]
	v_pk_fma_f32 v[190:191], v[104:105], v[16:17], v[128:129]
	v_pk_fma_f32 v[176:177], v[74:75], v[18:19], v[176:177]
	v_pk_fma_f32 v[178:179], v[76:77], v[20:21], v[178:179]
	v_pk_fma_f32 v[180:181], v[78:79], v[22:23], v[180:181]
	v_pk_fma_f32 v[182:183], v[80:81], v[24:25], v[182:183]
	v_pk_fma_f32 v[184:185], v[106:107], v[26:27], v[184:185]
	v_pk_fma_f32 v[186:187], v[108:109], v[28:29], v[186:187]
	v_pk_fma_f32 v[188:189], v[110:111], v[30:31], v[188:189]
	v_pk_fma_f32 v[190:191], v[112:113], v[32:33], v[190:191]
	v_pk_fma_f32 v[176:177], v[82:83], v[34:35], v[176:177]
	v_pk_fma_f32 v[178:179], v[84:85], v[36:37], v[178:179]
	v_pk_fma_f32 v[180:181], v[86:87], v[38:39], v[180:181]
	v_pk_fma_f32 v[182:183], v[88:89], v[40:41], v[182:183]
	v_pk_fma_f32 v[184:185], v[114:115], v[42:43], v[184:185]
	v_pk_fma_f32 v[186:187], v[116:117], v[44:45], v[186:187]
	v_pk_fma_f32 v[188:189], v[118:119], v[46:47], v[188:189]
	v_pk_fma_f32 v[190:191], v[120:121], v[48:49], v[190:191]
	v_pk_mul_f32 v[192:193], v[176:177], v[214:215]
	v_pk_mul_f32 v[194:195], v[178:179], v[214:215]
	v_pk_mul_f32 v[196:197], v[180:181], v[214:215]
	v_pk_mul_f32 v[198:199], v[182:183], v[214:215]
	v_exp_f32_e32 v192, v192
	v_exp_f32_e32 v193, v193
	v_exp_f32_e32 v194, v194
	v_exp_f32_e32 v195, v195
	v_exp_f32_e32 v196, v196
	v_exp_f32_e32 v197, v197
	v_exp_f32_e32 v198, v198
	v_exp_f32_e32 v199, v199
	v_pk_add_f32 v[192:193], v[192:193], 1.0 op_sel_hi:[1,0]
	v_pk_add_f32 v[194:195], v[194:195], 1.0 op_sel_hi:[1,0]
	v_pk_add_f32 v[196:197], v[196:197], 1.0 op_sel_hi:[1,0]
	v_pk_add_f32 v[198:199], v[198:199], 1.0 op_sel_hi:[1,0]
	v_rcp_f32_e32 v192, v192
	v_rcp_f32_e32 v193, v193
	v_rcp_f32_e32 v194, v194
	v_rcp_f32_e32 v195, v195
	v_rcp_f32_e32 v196, v196
	v_rcp_f32_e32 v197, v197
	v_rcp_f32_e32 v198, v198
	v_rcp_f32_e32 v199, v199
	s_waitcnt lgkmcnt(0)
	v_lshlrev_b32_e32 v50, 16, v204
	v_and_b32_e32 v51, 0xffff0000, v204
	v_lshlrev_b32_e32 v52, 16, v205
	v_and_b32_e32 v53, 0xffff0000, v205
	v_lshlrev_b32_e32 v54, 16, v206
	v_and_b32_e32 v55, 0xffff0000, v206
	v_lshlrev_b32_e32 v56, 16, v207
	v_and_b32_e32 v57, 0xffff0000, v207
	v_lshlrev_b32_e32 v58, 16, v210
	v_and_b32_e32 v59, 0xffff0000, v210
	v_lshlrev_b32_e32 v60, 16, v211
	v_and_b32_e32 v61, 0xffff0000, v211
	v_lshlrev_b32_e32 v62, 16, v212
	v_and_b32_e32 v63, 0xffff0000, v212
	v_lshlrev_b32_e32 v64, 16, v213
	v_and_b32_e32 v65, 0xffff0000, v213
	ds_read_b128 v[204:207], v222 offset:3696
	ds_read_b128 v[210:213], v222 offset:3824
	v_pk_mul_f32 v[176:177], v[176:177], v[192:193]
	v_pk_mul_f32 v[178:179], v[178:179], v[194:195]
	v_pk_mul_f32 v[180:181], v[180:181], v[196:197]
	v_pk_mul_f32 v[182:183], v[182:183], v[198:199]
	v_pk_mul_f32 v[176:177], v[176:177], v[184:185]
	v_pk_mul_f32 v[178:179], v[178:179], v[186:187]
	v_pk_mul_f32 v[180:181], v[180:181], v[188:189]
	v_pk_mul_f32 v[182:183], v[182:183], v[190:191]
	v_cvt_pk_bf16_f32 v200, v176, v177
	v_cvt_pk_bf16_f32 v201, v178, v179
	v_cvt_pk_bf16_f32 v202, v180, v181
	v_cvt_pk_bf16_f32 v203, v182, v183
	global_store_dwordx4 v223, v[200:203], s[0:1] sc1
	v_add_u32_e32 v223, 0x1600, v223
	v_pk_fma_f32 v[176:177], v[66:67], v[18:19], v[90:91]
	v_pk_fma_f32 v[178:179], v[68:69], v[20:21], v[92:93]
	v_pk_fma_f32 v[180:181], v[70:71], v[22:23], v[94:95]
	v_pk_fma_f32 v[182:183], v[72:73], v[24:25], v[96:97]
	v_pk_fma_f32 v[184:185], v[98:99], v[26:27], v[122:123]
	v_pk_fma_f32 v[186:187], v[100:101], v[28:29], v[124:125]
	v_pk_fma_f32 v[188:189], v[102:103], v[30:31], v[126:127]
	v_pk_fma_f32 v[190:191], v[104:105], v[32:33], v[128:129]
	v_pk_fma_f32 v[176:177], v[74:75], v[34:35], v[176:177]
	v_pk_fma_f32 v[178:179], v[76:77], v[36:37], v[178:179]
	v_pk_fma_f32 v[180:181], v[78:79], v[38:39], v[180:181]
	v_pk_fma_f32 v[182:183], v[80:81], v[40:41], v[182:183]
	v_pk_fma_f32 v[184:185], v[106:107], v[42:43], v[184:185]
	v_pk_fma_f32 v[186:187], v[108:109], v[44:45], v[186:187]
	v_pk_fma_f32 v[188:189], v[110:111], v[46:47], v[188:189]
	v_pk_fma_f32 v[190:191], v[112:113], v[48:49], v[190:191]
	v_pk_fma_f32 v[176:177], v[82:83], v[50:51], v[176:177]
	v_pk_fma_f32 v[178:179], v[84:85], v[52:53], v[178:179]
	v_pk_fma_f32 v[180:181], v[86:87], v[54:55], v[180:181]
	v_pk_fma_f32 v[182:183], v[88:89], v[56:57], v[182:183]
	v_pk_fma_f32 v[184:185], v[114:115], v[58:59], v[184:185]
	v_pk_fma_f32 v[186:187], v[116:117], v[60:61], v[186:187]
	v_pk_fma_f32 v[188:189], v[118:119], v[62:63], v[188:189]
	v_pk_fma_f32 v[190:191], v[120:121], v[64:65], v[190:191]
	v_pk_mul_f32 v[192:193], v[176:177], v[214:215]
	v_pk_mul_f32 v[194:195], v[178:179], v[214:215]
	v_pk_mul_f32 v[196:197], v[180:181], v[214:215]
	v_pk_mul_f32 v[198:199], v[182:183], v[214:215]
	v_exp_f32_e32 v192, v192
	v_exp_f32_e32 v193, v193
	v_exp_f32_e32 v194, v194
	v_exp_f32_e32 v195, v195
	v_exp_f32_e32 v196, v196
	v_exp_f32_e32 v197, v197
	v_exp_f32_e32 v198, v198
	v_exp_f32_e32 v199, v199
	v_pk_add_f32 v[192:193], v[192:193], 1.0 op_sel_hi:[1,0]
	v_pk_add_f32 v[194:195], v[194:195], 1.0 op_sel_hi:[1,0]
	v_pk_add_f32 v[196:197], v[196:197], 1.0 op_sel_hi:[1,0]
	v_pk_add_f32 v[198:199], v[198:199], 1.0 op_sel_hi:[1,0]
	v_rcp_f32_e32 v192, v192
	v_rcp_f32_e32 v193, v193
	v_rcp_f32_e32 v194, v194
	v_rcp_f32_e32 v195, v195
	v_rcp_f32_e32 v196, v196
	v_rcp_f32_e32 v197, v197
	v_rcp_f32_e32 v198, v198
	v_rcp_f32_e32 v199, v199
	s_waitcnt lgkmcnt(0)
	v_lshlrev_b32_e32 v2, 16, v204
	v_and_b32_e32 v3, 0xffff0000, v204
	v_lshlrev_b32_e32 v4, 16, v205
	v_and_b32_e32 v5, 0xffff0000, v205
	v_lshlrev_b32_e32 v6, 16, v206
	v_and_b32_e32 v7, 0xffff0000, v206
	v_lshlrev_b32_e32 v8, 16, v207
	v_and_b32_e32 v9, 0xffff0000, v207
	v_lshlrev_b32_e32 v10, 16, v210
	v_and_b32_e32 v11, 0xffff0000, v210
	v_lshlrev_b32_e32 v12, 16, v211
	v_and_b32_e32 v13, 0xffff0000, v211
	v_lshlrev_b32_e32 v14, 16, v212
	v_and_b32_e32 v15, 0xffff0000, v212
	v_lshlrev_b32_e32 v16, 16, v213
	v_and_b32_e32 v17, 0xffff0000, v213
	v_cmp_ne_u32_e32 vcc, 31, v224
	s_nop 1
	s_and_saveexec_b64 s[38:39], vcc
	ds_read_b128 v[204:207], v222 offset:4224
	ds_read_b128 v[210:213], v222 offset:4352
	s_or_b64 exec, exec, s[38:39]
	v_pk_mul_f32 v[176:177], v[176:177], v[192:193]
	v_pk_mul_f32 v[178:179], v[178:179], v[194:195]
	v_pk_mul_f32 v[180:181], v[180:181], v[196:197]
	v_pk_mul_f32 v[182:183], v[182:183], v[198:199]
	v_pk_mul_f32 v[176:177], v[176:177], v[184:185]
	v_pk_mul_f32 v[178:179], v[178:179], v[186:187]
	v_pk_mul_f32 v[180:181], v[180:181], v[188:189]
	v_pk_mul_f32 v[182:183], v[182:183], v[190:191]
	v_cvt_pk_bf16_f32 v200, v176, v177
	v_cvt_pk_bf16_f32 v201, v178, v179
	v_cvt_pk_bf16_f32 v202, v180, v181
	v_cvt_pk_bf16_f32 v203, v182, v183
	global_store_dwordx4 v223, v[200:203], s[0:1] sc1
	v_add_u32_e32 v223, 0x1600, v223
	v_pk_fma_f32 v[176:177], v[66:67], v[34:35], v[90:91]
	v_pk_fma_f32 v[178:179], v[68:69], v[36:37], v[92:93]
	v_pk_fma_f32 v[180:181], v[70:71], v[38:39], v[94:95]
	v_pk_fma_f32 v[182:183], v[72:73], v[40:41], v[96:97]
	v_pk_fma_f32 v[184:185], v[98:99], v[42:43], v[122:123]
	v_pk_fma_f32 v[186:187], v[100:101], v[44:45], v[124:125]
	v_pk_fma_f32 v[188:189], v[102:103], v[46:47], v[126:127]
	v_pk_fma_f32 v[190:191], v[104:105], v[48:49], v[128:129]
	v_pk_fma_f32 v[176:177], v[74:75], v[50:51], v[176:177]
	v_pk_fma_f32 v[178:179], v[76:77], v[52:53], v[178:179]
	v_pk_fma_f32 v[180:181], v[78:79], v[54:55], v[180:181]
	v_pk_fma_f32 v[182:183], v[80:81], v[56:57], v[182:183]
	v_pk_fma_f32 v[184:185], v[106:107], v[58:59], v[184:185]
	v_pk_fma_f32 v[186:187], v[108:109], v[60:61], v[186:187]
	v_pk_fma_f32 v[188:189], v[110:111], v[62:63], v[188:189]
	v_pk_fma_f32 v[190:191], v[112:113], v[64:65], v[190:191]
	v_pk_fma_f32 v[176:177], v[82:83], v[2:3], v[176:177]
	v_pk_fma_f32 v[178:179], v[84:85], v[4:5], v[178:179]
	v_pk_fma_f32 v[180:181], v[86:87], v[6:7], v[180:181]
	v_pk_fma_f32 v[182:183], v[88:89], v[8:9], v[182:183]
	v_pk_fma_f32 v[184:185], v[114:115], v[10:11], v[184:185]
	v_pk_fma_f32 v[186:187], v[116:117], v[12:13], v[186:187]
	v_pk_fma_f32 v[188:189], v[118:119], v[14:15], v[188:189]
	v_pk_fma_f32 v[190:191], v[120:121], v[16:17], v[190:191]
	v_pk_mul_f32 v[192:193], v[176:177], v[214:215]
	v_pk_mul_f32 v[194:195], v[178:179], v[214:215]
	v_pk_mul_f32 v[196:197], v[180:181], v[214:215]
	v_pk_mul_f32 v[198:199], v[182:183], v[214:215]
	v_exp_f32_e32 v192, v192
	v_exp_f32_e32 v193, v193
	v_exp_f32_e32 v194, v194
	v_exp_f32_e32 v195, v195
	v_exp_f32_e32 v196, v196
	v_exp_f32_e32 v197, v197
	v_exp_f32_e32 v198, v198
	v_exp_f32_e32 v199, v199
	v_pk_add_f32 v[192:193], v[192:193], 1.0 op_sel_hi:[1,0]
	v_pk_add_f32 v[194:195], v[194:195], 1.0 op_sel_hi:[1,0]
	v_pk_add_f32 v[196:197], v[196:197], 1.0 op_sel_hi:[1,0]
	v_pk_add_f32 v[198:199], v[198:199], 1.0 op_sel_hi:[1,0]
	v_rcp_f32_e32 v192, v192
	v_rcp_f32_e32 v193, v193
	v_rcp_f32_e32 v194, v194
	v_rcp_f32_e32 v195, v195
	v_rcp_f32_e32 v196, v196
	v_rcp_f32_e32 v197, v197
	v_rcp_f32_e32 v198, v198
	v_rcp_f32_e32 v199, v199
	s_waitcnt lgkmcnt(0)
	v_lshlrev_b32_e32 v18, 16, v204
	v_and_b32_e32 v19, 0xffff0000, v204
	v_lshlrev_b32_e32 v20, 16, v205
	v_and_b32_e32 v21, 0xffff0000, v205
	v_lshlrev_b32_e32 v22, 16, v206
	v_and_b32_e32 v23, 0xffff0000, v206
	v_lshlrev_b32_e32 v24, 16, v207
	v_and_b32_e32 v25, 0xffff0000, v207
	v_lshlrev_b32_e32 v26, 16, v210
	v_and_b32_e32 v27, 0xffff0000, v210
	v_lshlrev_b32_e32 v28, 16, v211
	v_and_b32_e32 v29, 0xffff0000, v211
	v_lshlrev_b32_e32 v30, 16, v212
	v_and_b32_e32 v31, 0xffff0000, v212
	v_lshlrev_b32_e32 v32, 16, v213
	v_and_b32_e32 v33, 0xffff0000, v213
	v_cmp_eq_u32_e32 vcc, 31, v224
	s_nop 1
	v_cndmask_b32_e64 v18, v18, 0, vcc
	v_cndmask_b32_e64 v19, v19, 0, vcc
	v_cndmask_b32_e64 v20, v20, 0, vcc
	v_cndmask_b32_e64 v21, v21, 0, vcc
	v_cndmask_b32_e64 v22, v22, 0, vcc
	v_cndmask_b32_e64 v23, v23, 0, vcc
	v_cndmask_b32_e64 v24, v24, 0, vcc
	v_cndmask_b32_e64 v25, v25, 0, vcc
	v_cndmask_b32_e64 v26, v26, 0, vcc
	v_cndmask_b32_e64 v27, v27, 0, vcc
	v_cndmask_b32_e64 v28, v28, 0, vcc
	v_cndmask_b32_e64 v29, v29, 0, vcc
	v_cndmask_b32_e64 v30, v30, 0, vcc
	v_cndmask_b32_e64 v31, v31, 0, vcc
	v_cndmask_b32_e64 v32, v32, 0, vcc
	v_cndmask_b32_e64 v33, v33, 0, vcc
	v_pk_mul_f32 v[176:177], v[176:177], v[192:193]
	v_pk_mul_f32 v[178:179], v[178:179], v[194:195]
	v_pk_mul_f32 v[180:181], v[180:181], v[196:197]
	v_pk_mul_f32 v[182:183], v[182:183], v[198:199]
	v_pk_mul_f32 v[176:177], v[176:177], v[184:185]
	v_pk_mul_f32 v[178:179], v[178:179], v[186:187]
	v_pk_mul_f32 v[180:181], v[180:181], v[188:189]
	v_pk_mul_f32 v[182:183], v[182:183], v[190:191]
	v_cvt_pk_bf16_f32 v200, v176, v177
	v_cvt_pk_bf16_f32 v201, v178, v179
	v_cvt_pk_bf16_f32 v202, v180, v181
	v_cvt_pk_bf16_f32 v203, v182, v183
	global_store_dwordx4 v223, v[200:203], s[0:1] sc1
	v_add_u32_e32 v223, 0x1600, v223
	v_pk_fma_f32 v[176:177], v[66:67], v[50:51], v[90:91]
	v_pk_fma_f32 v[178:179], v[68:69], v[52:53], v[92:93]
	v_pk_fma_f32 v[180:181], v[70:71], v[54:55], v[94:95]
	v_pk_fma_f32 v[182:183], v[72:73], v[56:57], v[96:97]
	v_pk_fma_f32 v[184:185], v[98:99], v[58:59], v[122:123]
	v_pk_fma_f32 v[186:187], v[100:101], v[60:61], v[124:125]
	v_pk_fma_f32 v[188:189], v[102:103], v[62:63], v[126:127]
	v_pk_fma_f32 v[190:191], v[104:105], v[64:65], v[128:129]
	v_pk_fma_f32 v[176:177], v[74:75], v[2:3], v[176:177]
	v_pk_fma_f32 v[178:179], v[76:77], v[4:5], v[178:179]
	v_pk_fma_f32 v[180:181], v[78:79], v[6:7], v[180:181]
	v_pk_fma_f32 v[182:183], v[80:81], v[8:9], v[182:183]
	v_pk_fma_f32 v[184:185], v[106:107], v[10:11], v[184:185]
	v_pk_fma_f32 v[186:187], v[108:109], v[12:13], v[186:187]
	v_pk_fma_f32 v[188:189], v[110:111], v[14:15], v[188:189]
	v_pk_fma_f32 v[190:191], v[112:113], v[16:17], v[190:191]
	v_pk_fma_f32 v[176:177], v[82:83], v[18:19], v[176:177]
	v_pk_fma_f32 v[178:179], v[84:85], v[20:21], v[178:179]
	v_pk_fma_f32 v[180:181], v[86:87], v[22:23], v[180:181]
	v_pk_fma_f32 v[182:183], v[88:89], v[24:25], v[182:183]
	v_pk_fma_f32 v[184:185], v[114:115], v[26:27], v[184:185]
	v_pk_fma_f32 v[186:187], v[116:117], v[28:29], v[186:187]
	v_pk_fma_f32 v[188:189], v[118:119], v[30:31], v[188:189]
	v_pk_fma_f32 v[190:191], v[120:121], v[32:33], v[190:191]
	v_pk_mul_f32 v[192:193], v[176:177], v[214:215]
	v_pk_mul_f32 v[194:195], v[178:179], v[214:215]
	v_pk_mul_f32 v[196:197], v[180:181], v[214:215]
	v_pk_mul_f32 v[198:199], v[182:183], v[214:215]
	v_exp_f32_e32 v192, v192
	v_exp_f32_e32 v193, v193
	v_exp_f32_e32 v194, v194
	v_exp_f32_e32 v195, v195
	v_exp_f32_e32 v196, v196
	v_exp_f32_e32 v197, v197
	v_exp_f32_e32 v198, v198
	v_exp_f32_e32 v199, v199
	v_pk_add_f32 v[192:193], v[192:193], 1.0 op_sel_hi:[1,0]
	v_pk_add_f32 v[194:195], v[194:195], 1.0 op_sel_hi:[1,0]
	v_pk_add_f32 v[196:197], v[196:197], 1.0 op_sel_hi:[1,0]
	v_pk_add_f32 v[198:199], v[198:199], 1.0 op_sel_hi:[1,0]
	v_rcp_f32_e32 v192, v192
	v_rcp_f32_e32 v193, v193
	v_rcp_f32_e32 v194, v194
	v_rcp_f32_e32 v195, v195
	v_rcp_f32_e32 v196, v196
	v_rcp_f32_e32 v197, v197
	v_rcp_f32_e32 v198, v198
	v_rcp_f32_e32 v199, v199
	v_pk_mul_f32 v[176:177], v[176:177], v[192:193]
	v_pk_mul_f32 v[178:179], v[178:179], v[194:195]
	v_pk_mul_f32 v[180:181], v[180:181], v[196:197]
	v_pk_mul_f32 v[182:183], v[182:183], v[198:199]
	v_pk_mul_f32 v[176:177], v[176:177], v[184:185]
	v_pk_mul_f32 v[178:179], v[178:179], v[186:187]
	v_pk_mul_f32 v[180:181], v[180:181], v[188:189]
	v_pk_mul_f32 v[182:183], v[182:183], v[190:191]
	v_cvt_pk_bf16_f32 v200, v176, v177
	v_cvt_pk_bf16_f32 v201, v178, v179
	v_cvt_pk_bf16_f32 v202, v180, v181
	v_cvt_pk_bf16_f32 v203, v182, v183
	s_and_b32 s36, s35, 3
	s_cmp_eq_u32 s36, 3
	s_cselect_b64 s[38:39], -1, 0
	s_cmp_lt_i32 s35, 32
	s_cselect_b64 vcc, -1, 0
	s_or_b64 s[38:39], s[38:39], vcc
	v_cmp_ne_u32_e32 vcc, 31, v224
	s_nop 1
	s_or_b64 vcc, vcc, s[38:39]
	s_and_saveexec_b64 s[38:39], vcc
	global_store_dwordx4 v223, v[200:203], s[0:1] sc1
	s_or_b64 exec, exec, s[38:39]
	v_mov_b32_e32 v74, v0
	s_cmp_lt_i32 s35, 32
	s_cselect_b64 s[6:7], -1, 0
	s_mov_b64 s[8:9], exec

.LBB0_1794:
	v_lshl_or_b32 v138, v172, 2, s40
	v_mad_u64_u32 v[150:151], s[4:5], v1, s47, v[138:139]
	v_cvt_pk_bf16_f32 v106, v106, v107
	v_cvt_pk_bf16_f32 v107, v108, v109
	v_cvt_pk_bf16_f32 v98, v98, v99
	v_cvt_pk_bf16_f32 v99, v100, v101
	v_cvt_pk_bf16_f32 v74, v74, v75
	s_nop 0
	v_lshl_add_u32 v1, v150, 1, 0
	v_add_u32_e32 v108, 0x4000, v1
	v_add_u32_e32 v100, 0x6000, v1
	v_cvt_pk_bf16_f32 v66, v66, v67
	v_cvt_pk_bf16_f32 v58, v58, v59
	v_cvt_pk_bf16_f32 v59, v60, v61
	v_add_u32_e32 v60, 0x10820, v1
	v_cvt_pk_bf16_f32 v50, v50, v51
	v_cvt_pk_bf16_f32 v51, v52, v53
	v_add_u32_e32 v52, 0x12920, v1
	v_cvt_pk_bf16_f32 v42, v42, v43
	v_cvt_pk_bf16_f32 v43, v44, v45
	v_add_u32_e32 v44, 0x14a20, v1
	v_cvt_pk_bf16_f32 v34, v34, v35
	v_cvt_pk_bf16_f32 v35, v36, v37
	v_add_u32_e32 v36, 0x16b20, v1
	v_cvt_pk_bf16_f32 v26, v26, v27
	v_cvt_pk_bf16_f32 v27, v28, v29
	v_add_u32_e32 v28, 0x10920, v1
	v_cvt_pk_bf16_f32 v18, v18, v19
	v_cvt_pk_bf16_f32 v19, v20, v21
	v_add_u32_e32 v20, 0x12a20, v1
	v_cvt_pk_bf16_f32 v10, v10, v11
	v_cvt_pk_bf16_f32 v11, v12, v13
	v_add_u32_e32 v12, 0x14b20, v1
	v_cvt_pk_bf16_f32 v126, v126, v127
	v_cvt_pk_bf16_f32 v127, v128, v129
	v_cvt_pk_bf16_f32 v122, v122, v123
	v_cvt_pk_bf16_f32 v123, v124, v125
	ds_write2_b64 v1, v[126:127], v[122:123] offset1:4
	v_cvt_pk_bf16_f32 v114, v114, v115
	v_cvt_pk_bf16_f32 v115, v116, v117
	v_add_u32_e32 v116, 0x2000, v1
	v_cvt_pk_bf16_f32 v94, v94, v95
	v_cvt_pk_bf16_f32 v95, v96, v97
	v_cvt_pk_bf16_f32 v90, v90, v91
	v_cvt_pk_bf16_f32 v91, v92, v93
	ds_write2_b64 v1, v[94:95], v[90:91] offset0:32 offset1:36
	v_cvt_pk_bf16_f32 v78, v78, v79
	v_cvt_pk_bf16_f32 v79, v80, v81
	v_cvt_pk_bf16_f32 v75, v76, v77
	ds_write2_b64 v108, v[78:79], v[74:75] offset0:96 offset1:100
	v_cvt_pk_bf16_f32 v70, v70, v71
	v_cvt_pk_bf16_f32 v71, v72, v73
	v_cvt_pk_bf16_f32 v67, v68, v69
	ds_write2_b64 v100, v[70:71], v[66:67] offset0:128 offset1:132
	v_add_u32_e32 v66, 0x10800, v1
	ds_write_b64 v60, v[58:59]
	v_add_u32_e32 v58, 0x12900, v1
	ds_write_b64 v52, v[50:51]
	v_add_u32_e32 v50, 0x14a00, v1
	ds_write_b64 v44, v[42:43]
	v_add_u32_e32 v42, 0x16b00, v1
	ds_write_b64 v36, v[34:35]
	v_add_u32_e32 v34, 0x10900, v1
	ds_write_b64 v28, v[26:27]
	v_add_u32_e32 v26, 0x12a00, v1
	ds_write_b64 v20, v[18:19]
	v_add_u32_e32 v18, 0x14b00, v1
	ds_write_b64 v12, v[10:11]
	v_add_u32_e32 v10, 0x16c00, v1
	v_cvt_pk_bf16_f32 v2, v2, v3
	v_add_u32_e32 v1, 0x16c20, v1
	v_mov_b32_e32 v74, v0
	v_cvt_pk_bf16_f32 v118, v118, v119
	v_cvt_pk_bf16_f32 v119, v120, v121
	ds_write2_b64 v116, v[118:119], v[114:115] offset0:32 offset1:36
	v_cvt_pk_bf16_f32 v110, v110, v111
	v_cvt_pk_bf16_f32 v111, v112, v113
	ds_write2_b64 v108, v[110:111], v[106:107] offset0:64 offset1:68
	v_cvt_pk_bf16_f32 v102, v102, v103
	v_cvt_pk_bf16_f32 v103, v104, v105
	ds_write2_b64 v100, v[102:103], v[98:99] offset0:96 offset1:100
	v_cvt_pk_bf16_f32 v86, v86, v87
	v_cvt_pk_bf16_f32 v87, v88, v89
	v_cvt_pk_bf16_f32 v82, v82, v83
	v_cvt_pk_bf16_f32 v83, v84, v85
	ds_write2_b64 v116, v[86:87], v[82:83] offset0:64 offset1:68
	v_cvt_pk_bf16_f32 v62, v62, v63
	v_cvt_pk_bf16_f32 v63, v64, v65
	ds_write_b64 v66, v[62:63]
	v_cvt_pk_bf16_f32 v54, v54, v55
	v_cvt_pk_bf16_f32 v55, v56, v57
	ds_write_b64 v58, v[54:55]
	v_cvt_pk_bf16_f32 v46, v46, v47
	v_cvt_pk_bf16_f32 v47, v48, v49
	ds_write_b64 v50, v[46:47]
	v_cvt_pk_bf16_f32 v38, v38, v39
	v_cvt_pk_bf16_f32 v39, v40, v41
	ds_write_b64 v42, v[38:39]
	v_cvt_pk_bf16_f32 v30, v30, v31
	v_cvt_pk_bf16_f32 v31, v32, v33
	ds_write_b64 v34, v[30:31]
	v_cvt_pk_bf16_f32 v22, v22, v23
	v_cvt_pk_bf16_f32 v23, v24, v25
	ds_write_b64 v26, v[22:23]
	v_cvt_pk_bf16_f32 v14, v14, v15
	v_cvt_pk_bf16_f32 v15, v16, v17
	ds_write_b64 v18, v[14:15]
	v_cvt_pk_bf16_f32 v6, v6, v7
	v_cvt_pk_bf16_f32 v7, v8, v9
	ds_write_b64 v10, v[6:7]
	v_cvt_pk_bf16_f32 v3, v4, v5
	ds_write_b64 v1, v[2:3]
	s_waitcnt lgkmcnt(0)
	s_barrier
	v_and_b32_e32 v225, 15, v0
	v_lshrrev_b32_e32 v224, 4, v0
	v_lshrrev_b32_e32 v222, 3, v225
	v_and_b32_e32 v225, 7, v225
	v_lshlrev_b32_e32 v225, 3, v225
	s_lshl_b32 s34, s15, 7
	v_lshl_or_b32 v216, v222, 6, v225
	v_or_b32_e32 v216, s34, v216
	v_lshl_or_b32 v222, v222, 7, v225
	v_lshlrev_b32_e32 v222, 1, v222
	v_mul_u32_u24_e32 v225, 0x1080, v224
	v_add_u32_e32 v222, v222, v225
	s_lshl_b32 s34, s35, 8
	v_lshl_add_u32 v223, v224, 3, s34
	v_mul_u32_u24_e32 v223, 0x1600, v223
	v_lshl_add_u32 v223, v216, 1, v223
	v_lshlrev_b32_e32 v216, 2, v216
	v_add_u32_e32 v217, 0x5800, v216
	v_add_u32_e32 v218, 0xb000, v216
	v_add_u32_e32 v219, 0x2c00, v216
	v_add_u32_e32 v220, 0x8400, v216
	v_add_u32_e32 v221, 0xdc00, v216
	global_load_dwordx4 v[66:69], v216, s[0:1]
	global_load_dwordx4 v[70:73], v216, s[0:1] offset:16
	global_load_dwordx4 v[74:77], v217, s[0:1]
	global_load_dwordx4 v[78:81], v217, s[0:1] offset:16
	global_load_dwordx4 v[82:85], v218, s[0:1]
	global_load_dwordx4 v[86:89], v218, s[0:1] offset:16
	global_load_dwordx4 v[98:101], v219, s[0:1]
	global_load_dwordx4 v[102:105], v219, s[0:1] offset:16
	global_load_dwordx4 v[106:109], v220, s[0:1]
	global_load_dwordx4 v[110:113], v220, s[0:1] offset:16
	global_load_dwordx4 v[114:117], v221, s[0:1]
	global_load_dwordx4 v[118:121], v221, s[0:1] offset:16
	global_load_dwordx4 v[90:93], v216, s[10:11]
	global_load_dwordx4 v[94:97], v216, s[10:11] offset:16
	global_load_dwordx4 v[122:125], v219, s[10:11]
	global_load_dwordx4 v[126:129], v219, s[10:11] offset:16
	v_mov_b32_e32 v214, 0xbfb8aa3b
	v_mov_b32_e32 v215, 0xbfb8aa3b
	v_cmp_ne_u32_e32 vcc, 0, v224
	s_nop 1
	s_and_saveexec_b64 s[38:39], vcc
	v_add_u32_e32 v225, 0xfffffdf0, v222
	ds_read_b128 v[204:207], v225
	ds_read_b128 v[210:213], v225 offset:128
	s_or_b64 exec, exec, s[38:39]
	s_waitcnt lgkmcnt(0)
	v_lshlrev_b32_e32 v2, 16, v204
	v_and_b32_e32 v3, 0xffff0000, v204
	v_lshlrev_b32_e32 v4, 16, v205
	v_and_b32_e32 v5, 0xffff0000, v205
	v_lshlrev_b32_e32 v6, 16, v206
	v_and_b32_e32 v7, 0xffff0000, v206
	v_lshlrev_b32_e32 v8, 16, v207
	v_and_b32_e32 v9, 0xffff0000, v207
	v_lshlrev_b32_e32 v10, 16, v210
	v_and_b32_e32 v11, 0xffff0000, v210
	v_lshlrev_b32_e32 v12, 16, v211
	v_and_b32_e32 v13, 0xffff0000, v211
	v_lshlrev_b32_e32 v14, 16, v212
	v_and_b32_e32 v15, 0xffff0000, v212
	v_lshlrev_b32_e32 v16, 16, v213
	v_and_b32_e32 v17, 0xffff0000, v213
	v_cmp_eq_u32_e32 vcc, 0, v224
	s_nop 1
	v_cndmask_b32_e64 v2, v2, 0, vcc
	v_cndmask_b32_e64 v3, v3, 0, vcc
	v_cndmask_b32_e64 v4, v4, 0, vcc
	v_cndmask_b32_e64 v5, v5, 0, vcc
	v_cndmask_b32_e64 v6, v6, 0, vcc
	v_cndmask_b32_e64 v7, v7, 0, vcc
	v_cndmask_b32_e64 v8, v8, 0, vcc
	v_cndmask_b32_e64 v9, v9, 0, vcc
	v_cndmask_b32_e64 v10, v10, 0, vcc
	v_cndmask_b32_e64 v11, v11, 0, vcc
	v_cndmask_b32_e64 v12, v12, 0, vcc
	v_cndmask_b32_e64 v13, v13, 0, vcc
	v_cndmask_b32_e64 v14, v14, 0, vcc
	v_cndmask_b32_e64 v15, v15, 0, vcc
	v_cndmask_b32_e64 v16, v16, 0, vcc
	v_cndmask_b32_e64 v17, v17, 0, vcc
	ds_read_b128 v[204:207], v222
	ds_read_b128 v[210:213], v222 offset:128
	s_waitcnt lgkmcnt(0)
	v_lshlrev_b32_e32 v18, 16, v204
	v_and_b32_e32 v19, 0xffff0000, v204
	v_lshlrev_b32_e32 v20, 16, v205
	v_and_b32_e32 v21, 0xffff0000, v205
	v_lshlrev_b32_e32 v22, 16, v206
	v_and_b32_e32 v23, 0xffff0000, v206
	v_lshlrev_b32_e32 v24, 16, v207
	v_and_b32_e32 v25, 0xffff0000, v207
	v_lshlrev_b32_e32 v26, 16, v210
	v_and_b32_e32 v27, 0xffff0000, v210
	v_lshlrev_b32_e32 v28, 16, v211
	v_and_b32_e32 v29, 0xffff0000, v211
	v_lshlrev_b32_e32 v30, 16, v212
	v_and_b32_e32 v31, 0xffff0000, v212
	v_lshlrev_b32_e32 v32, 16, v213
	v_and_b32_e32 v33, 0xffff0000, v213
	ds_read_b128 v[204:207], v222 offset:528
	ds_read_b128 v[210:213], v222 offset:656
	s_waitcnt lgkmcnt(0)
	v_lshlrev_b32_e32 v34, 16, v204
	v_and_b32_e32 v35, 0xffff0000, v204
	v_lshlrev_b32_e32 v36, 16, v205
	v_and_b32_e32 v37, 0xffff0000, v205
	v_lshlrev_b32_e32 v38, 16, v206
	v_and_b32_e32 v39, 0xffff0000, v206
	v_lshlrev_b32_e32 v40, 16, v207
	v_and_b32_e32 v41, 0xffff0000, v207
	v_lshlrev_b32_e32 v42, 16, v210
	v_and_b32_e32 v43, 0xffff0000, v210
	v_lshlrev_b32_e32 v44, 16, v211
	v_and_b32_e32 v45, 0xffff0000, v211
	v_lshlrev_b32_e32 v46, 16, v212
	v_and_b32_e32 v47, 0xffff0000, v212
	v_lshlrev_b32_e32 v48, 16, v213
	v_and_b32_e32 v49, 0xffff0000, v213
	ds_read_b128 v[204:207], v222 offset:1056
	ds_read_b128 v[210:213], v222 offset:1184
	s_waitcnt vmcnt(0)
	v_pk_fma_f32 v[176:177], v[66:67], v[2:3], v[90:91]
	v_pk_fma_f32 v[178:179], v[68:69], v[4:5], v[92:93]
	v_pk_fma_f32 v[180:181], v[70:71], v[6:7], v[94:95]
	v_pk_fma_f32 v[182:183], v[72:73], v[8:9], v[96:97]
	v_pk_fma_f32 v[184:185], v[98:99], v[10:11], v[122:123]
	v_pk_fma_f32 v[186:187], v[100:101], v[12:13], v[124:125]
	v_pk_fma_f32 v[188:189], v[102:103], v[14:15], v[126:127]
	v_pk_fma_f32 v[190:191], v[104:105], v[16:17], v[128:129]
	v_pk_fma_f32 v[176:177], v[74:75], v[18:19], v[176:177]
	v_pk_fma_f32 v[178:179], v[76:77], v[20:21], v[178:179]
	v_pk_fma_f32 v[180:181], v[78:79], v[22:23], v[180:181]
	v_pk_fma_f32 v[182:183], v[80:81], v[24:25], v[182:183]
	v_pk_fma_f32 v[184:185], v[106:107], v[26:27], v[184:185]
	v_pk_fma_f32 v[186:187], v[108:109], v[28:29], v[186:187]
	v_pk_fma_f32 v[188:189], v[110:111], v[30:31], v[188:189]
	v_pk_fma_f32 v[190:191], v[112:113], v[32:33], v[190:191]
	v_pk_fma_f32 v[176:177], v[82:83], v[34:35], v[176:177]
	v_pk_fma_f32 v[178:179], v[84:85], v[36:37], v[178:179]
	v_pk_fma_f32 v[180:181], v[86:87], v[38:39], v[180:181]
	v_pk_fma_f32 v[182:183], v[88:89], v[40:41], v[182:183]
	v_pk_fma_f32 v[184:185], v[114:115], v[42:43], v[184:185]
	v_pk_fma_f32 v[186:187], v[116:117], v[44:45], v[186:187]
	v_pk_fma_f32 v[188:189], v[118:119], v[46:47], v[188:189]
	v_pk_fma_f32 v[190:191], v[120:121], v[48:49], v[190:191]
	v_pk_mul_f32 v[192:193], v[176:177], v[214:215]
	v_pk_mul_f32 v[194:195], v[178:179], v[214:215]
	v_pk_mul_f32 v[196:197], v[180:181], v[214:215]
	v_pk_mul_f32 v[198:199], v[182:183], v[214:215]
	v_exp_f32_e32 v192, v192
	v_exp_f32_e32 v193, v193
	v_exp_f32_e32 v194, v194
	v_exp_f32_e32 v195, v195
	v_exp_f32_e32 v196, v196
	v_exp_f32_e32 v197, v197
	v_exp_f32_e32 v198, v198
	v_exp_f32_e32 v199, v199
	v_pk_add_f32 v[192:193], v[192:193], 1.0 op_sel_hi:[1,0]
	v_pk_add_f32 v[194:195], v[194:195], 1.0 op_sel_hi:[1,0]
	v_pk_add_f32 v[196:197], v[196:197], 1.0 op_sel_hi:[1,0]
	v_pk_add_f32 v[198:199], v[198:199], 1.0 op_sel_hi:[1,0]
	v_rcp_f32_e32 v192, v192
	v_rcp_f32_e32 v193, v193
	v_rcp_f32_e32 v194, v194
	v_rcp_f32_e32 v195, v195
	v_rcp_f32_e32 v196, v196
	v_rcp_f32_e32 v197, v197
	v_rcp_f32_e32 v198, v198
	v_rcp_f32_e32 v199, v199
	s_waitcnt lgkmcnt(0)
	v_lshlrev_b32_e32 v50, 16, v204
	v_and_b32_e32 v51, 0xffff0000, v204
	v_lshlrev_b32_e32 v52, 16, v205
	v_and_b32_e32 v53, 0xffff0000, v205
	v_lshlrev_b32_e32 v54, 16, v206
	v_and_b32_e32 v55, 0xffff0000, v206
	v_lshlrev_b32_e32 v56, 16, v207
	v_and_b32_e32 v57, 0xffff0000, v207
	v_lshlrev_b32_e32 v58, 16, v210
	v_and_b32_e32 v59, 0xffff0000, v210
	v_lshlrev_b32_e32 v60, 16, v211
	v_and_b32_e32 v61, 0xffff0000, v211
	v_lshlrev_b32_e32 v62, 16, v212
	v_and_b32_e32 v63, 0xffff0000, v212
	v_lshlrev_b32_e32 v64, 16, v213
	v_and_b32_e32 v65, 0xffff0000, v213
	ds_read_b128 v[204:207], v222 offset:1584
	ds_read_b128 v[210:213], v222 offset:1712
	v_pk_mul_f32 v[176:177], v[176:177], v[192:193]
	v_pk_mul_f32 v[178:179], v[178:179], v[194:195]
	v_pk_mul_f32 v[180:181], v[180:181], v[196:197]
	v_pk_mul_f32 v[182:183], v[182:183], v[198:199]
	v_pk_mul_f32 v[176:177], v[176:177], v[184:185]
	v_pk_mul_f32 v[178:179], v[178:179], v[186:187]
	v_pk_mul_f32 v[180:181], v[180:181], v[188:189]
	v_pk_mul_f32 v[182:183], v[182:183], v[190:191]
	v_cvt_pk_bf16_f32 v200, v176, v177
	v_cvt_pk_bf16_f32 v201, v178, v179
	v_cvt_pk_bf16_f32 v202, v180, v181
	v_cvt_pk_bf16_f32 v203, v182, v183
	s_and_b32 s36, s35, 3
	s_cmp_eq_u32 s36, 0
	s_cselect_b64 s[38:39], -1, 0
	s_cmp_lt_i32 s35, 32
	s_cselect_b64 vcc, -1, 0
	s_or_b64 s[38:39], s[38:39], vcc
	v_cmp_ne_u32_e32 vcc, 0, v224
	s_nop 1
	s_or_b64 vcc, vcc, s[38:39]
	s_and_saveexec_b64 s[38:39], vcc
	global_store_dwordx4 v223, v[200:203], s[12:13] sc1
	s_or_b64 exec, exec, s[38:39]
	v_add_u32_e32 v223, 0x1600, v223
	v_pk_fma_f32 v[176:177], v[66:67], v[18:19], v[90:91]
	v_pk_fma_f32 v[178:179], v[68:69], v[20:21], v[92:93]
	v_pk_fma_f32 v[180:181], v[70:71], v[22:23], v[94:95]
	v_pk_fma_f32 v[182:183], v[72:73], v[24:25], v[96:97]
	v_pk_fma_f32 v[184:185], v[98:99], v[26:27], v[122:123]
	v_pk_fma_f32 v[186:187], v[100:101], v[28:29], v[124:125]
	v_pk_fma_f32 v[188:189], v[102:103], v[30:31], v[126:127]
	v_pk_fma_f32 v[190:191], v[104:105], v[32:33], v[128:129]
	v_pk_fma_f32 v[176:177], v[74:75], v[34:35], v[176:177]
	v_pk_fma_f32 v[178:179], v[76:77], v[36:37], v[178:179]
	v_pk_fma_f32 v[180:181], v[78:79], v[38:39], v[180:181]
	v_pk_fma_f32 v[182:183], v[80:81], v[40:41], v[182:183]
	v_pk_fma_f32 v[184:185], v[106:107], v[42:43], v[184:185]
	v_pk_fma_f32 v[186:187], v[108:109], v[44:45], v[186:187]
	v_pk_fma_f32 v[188:189], v[110:111], v[46:47], v[188:189]
	v_pk_fma_f32 v[190:191], v[112:113], v[48:49], v[190:191]
	v_pk_fma_f32 v[176:177], v[82:83], v[50:51], v[176:177]
	v_pk_fma_f32 v[178:179], v[84:85], v[52:53], v[178:179]
	v_pk_fma_f32 v[180:181], v[86:87], v[54:55], v[180:181]
	v_pk_fma_f32 v[182:183], v[88:89], v[56:57], v[182:183]
	v_pk_fma_f32 v[184:185], v[114:115], v[58:59], v[184:185]
	v_pk_fma_f32 v[186:187], v[116:117], v[60:61], v[186:187]
	v_pk_fma_f32 v[188:189], v[118:119], v[62:63], v[188:189]
	v_pk_fma_f32 v[190:191], v[120:121], v[64:65], v[190:191]
	v_pk_mul_f32 v[192:193], v[176:177], v[214:215]
	v_pk_mul_f32 v[194:195], v[178:179], v[214:215]
	v_pk_mul_f32 v[196:197], v[180:181], v[214:215]
	v_pk_mul_f32 v[198:199], v[182:183], v[214:215]
	v_exp_f32_e32 v192, v192
	v_exp_f32_e32 v193, v193
	v_exp_f32_e32 v194, v194
	v_exp_f32_e32 v195, v195
	v_exp_f32_e32 v196, v196
	v_exp_f32_e32 v197, v197
	v_exp_f32_e32 v198, v198
	v_exp_f32_e32 v199, v199
	v_pk_add_f32 v[192:193], v[192:193], 1.0 op_sel_hi:[1,0]
	v_pk_add_f32 v[194:195], v[194:195], 1.0 op_sel_hi:[1,0]
	v_pk_add_f32 v[196:197], v[196:197], 1.0 op_sel_hi:[1,0]
	v_pk_add_f32 v[198:199], v[198:199], 1.0 op_sel_hi:[1,0]
	v_rcp_f32_e32 v192, v192
	v_rcp_f32_e32 v193, v193
	v_rcp_f32_e32 v194, v194
	v_rcp_f32_e32 v195, v195
	v_rcp_f32_e32 v196, v196
	v_rcp_f32_e32 v197, v197
	v_rcp_f32_e32 v198, v198
	v_rcp_f32_e32 v199, v199
	s_waitcnt lgkmcnt(0)
	v_lshlrev_b32_e32 v2, 16, v204
	v_and_b32_e32 v3, 0xffff0000, v204
	v_lshlrev_b32_e32 v4, 16, v205
	v_and_b32_e32 v5, 0xffff0000, v205
	v_lshlrev_b32_e32 v6, 16, v206
	v_and_b32_e32 v7, 0xffff0000, v206
	v_lshlrev_b32_e32 v8, 16, v207
	v_and_b32_e32 v9, 0xffff0000, v207
	v_lshlrev_b32_e32 v10, 16, v210
	v_and_b32_e32 v11, 0xffff0000, v210
	v_lshlrev_b32_e32 v12, 16, v211
	v_and_b32_e32 v13, 0xffff0000, v211
	v_lshlrev_b32_e32 v14, 16, v212
	v_and_b32_e32 v15, 0xffff0000, v212
	v_lshlrev_b32_e32 v16, 16, v213
	v_and_b32_e32 v17, 0xffff0000, v213
	ds_read_b128 v[204:207], v222 offset:2112
	ds_read_b128 v[210:213], v222 offset:2240
	v_pk_mul_f32 v[176:177], v[176:177], v[192:193]
	v_pk_mul_f32 v[178:179], v[178:179], v[194:195]
	v_pk_mul_f32 v[180:181], v[180:181], v[196:197]
	v_pk_mul_f32 v[182:183], v[182:183], v[198:199]
	v_pk_mul_f32 v[176:177], v[176:177], v[184:185]
	v_pk_mul_f32 v[178:179], v[178:179], v[186:187]
	v_pk_mul_f32 v[180:181], v[180:181], v[188:189]
	v_pk_mul_f32 v[182:183], v[182:183], v[190:191]
	v_cvt_pk_bf16_f32 v200, v176, v177
	v_cvt_pk_bf16_f32 v201, v178, v179
	v_cvt_pk_bf16_f32 v202, v180, v181
	v_cvt_pk_bf16_f32 v203, v182, v183
	global_store_dwordx4 v223, v[200:203], s[12:13] sc1
	v_add_u32_e32 v223, 0x1600, v223
	v_pk_fma_f32 v[176:177], v[66:67], v[34:35], v[90:91]
	v_pk_fma_f32 v[178:179], v[68:69], v[36:37], v[92:93]
	v_pk_fma_f32 v[180:181], v[70:71], v[38:39], v[94:95]
	v_pk_fma_f32 v[182:183], v[72:73], v[40:41], v[96:97]
	v_pk_fma_f32 v[184:185], v[98:99], v[42:43], v[122:123]
	v_pk_fma_f32 v[186:187], v[100:101], v[44:45], v[124:125]
	v_pk_fma_f32 v[188:189], v[102:103], v[46:47], v[126:127]
	v_pk_fma_f32 v[190:191], v[104:105], v[48:49], v[128:129]
	v_pk_fma_f32 v[176:177], v[74:75], v[50:51], v[176:177]
	v_pk_fma_f32 v[178:179], v[76:77], v[52:53], v[178:179]
	v_pk_fma_f32 v[180:181], v[78:79], v[54:55], v[180:181]
	v_pk_fma_f32 v[182:183], v[80:81], v[56:57], v[182:183]
	v_pk_fma_f32 v[184:185], v[106:107], v[58:59], v[184:185]
	v_pk_fma_f32 v[186:187], v[108:109], v[60:61], v[186:187]
	v_pk_fma_f32 v[188:189], v[110:111], v[62:63], v[188:189]
	v_pk_fma_f32 v[190:191], v[112:113], v[64:65], v[190:191]
	v_pk_fma_f32 v[176:177], v[82:83], v[2:3], v[176:177]
	v_pk_fma_f32 v[178:179], v[84:85], v[4:5], v[178:179]
	v_pk_fma_f32 v[180:181], v[86:87], v[6:7], v[180:181]
	v_pk_fma_f32 v[182:183], v[88:89], v[8:9], v[182:183]
	v_pk_fma_f32 v[184:185], v[114:115], v[10:11], v[184:185]
	v_pk_fma_f32 v[186:187], v[116:117], v[12:13], v[186:187]
	v_pk_fma_f32 v[188:189], v[118:119], v[14:15], v[188:189]
	v_pk_fma_f32 v[190:191], v[120:121], v[16:17], v[190:191]
	v_pk_mul_f32 v[192:193], v[176:177], v[214:215]
	v_pk_mul_f32 v[194:195], v[178:179], v[214:215]
	v_pk_mul_f32 v[196:197], v[180:181], v[214:215]
	v_pk_mul_f32 v[198:199], v[182:183], v[214:215]
	v_exp_f32_e32 v192, v192
	v_exp_f32_e32 v193, v193
	v_exp_f32_e32 v194, v194
	v_exp_f32_e32 v195, v195
	v_exp_f32_e32 v196, v196
	v_exp_f32_e32 v197, v197
	v_exp_f32_e32 v198, v198
	v_exp_f32_e32 v199, v199
	v_pk_add_f32 v[192:193], v[192:193], 1.0 op_sel_hi:[1,0]
	v_pk_add_f32 v[194:195], v[194:195], 1.0 op_sel_hi:[1,0]
	v_pk_add_f32 v[196:197], v[196:197], 1.0 op_sel_hi:[1,0]
	v_pk_add_f32 v[198:199], v[198:199], 1.0 op_sel_hi:[1,0]
	v_rcp_f32_e32 v192, v192
	v_rcp_f32_e32 v193, v193
	v_rcp_f32_e32 v194, v194
	v_rcp_f32_e32 v195, v195
	v_rcp_f32_e32 v196, v196
	v_rcp_f32_e32 v197, v197
	v_rcp_f32_e32 v198, v198
	v_rcp_f32_e32 v199, v199
	s_waitcnt lgkmcnt(0)
	v_lshlrev_b32_e32 v18, 16, v204
	v_and_b32_e32 v19, 0xffff0000, v204
	v_lshlrev_b32_e32 v20, 16, v205
	v_and_b32_e32 v21, 0xffff0000, v205
	v_lshlrev_b32_e32 v22, 16, v206
	v_and_b32_e32 v23, 0xffff0000, v206
	v_lshlrev_b32_e32 v24, 16, v207
	v_and_b32_e32 v25, 0xffff0000, v207
	v_lshlrev_b32_e32 v26, 16, v210
	v_and_b32_e32 v27, 0xffff0000, v210
	v_lshlrev_b32_e32 v28, 16, v211
	v_and_b32_e32 v29, 0xffff0000, v211
	v_lshlrev_b32_e32 v30, 16, v212
	v_and_b32_e32 v31, 0xffff0000, v212
	v_lshlrev_b32_e32 v32, 16, v213
	v_and_b32_e32 v33, 0xffff0000, v213
	ds_read_b128 v[204:207], v222 offset:2640
	ds_read_b128 v[210:213], v222 offset:2768
	v_pk_mul_f32 v[176:177], v[176:177], v[192:193]
	v_pk_mul_f32 v[178:179], v[178:179], v[194:195]
	v_pk_mul_f32 v[180:181], v[180:181], v[196:197]
	v_pk_mul_f32 v[182:183], v[182:183], v[198:199]
	v_pk_mul_f32 v[176:177], v[176:177], v[184:185]
	v_pk_mul_f32 v[178:179], v[178:179], v[186:187]
	v_pk_mul_f32 v[180:181], v[180:181], v[188:189]
	v_pk_mul_f32 v[182:183], v[182:183], v[190:191]
	v_cvt_pk_bf16_f32 v200, v176, v177
	v_cvt_pk_bf16_f32 v201, v178, v179
	v_cvt_pk_bf16_f32 v202, v180, v181
	v_cvt_pk_bf16_f32 v203, v182, v183
	global_store_dwordx4 v223, v[200:203], s[12:13] sc1
	v_add_u32_e32 v223, 0x1600, v223
	v_pk_fma_f32 v[176:177], v[66:67], v[50:51], v[90:91]
	v_pk_fma_f32 v[178:179], v[68:69], v[52:53], v[92:93]
	v_pk_fma_f32 v[180:181], v[70:71], v[54:55], v[94:95]
	v_pk_fma_f32 v[182:183], v[72:73], v[56:57], v[96:97]
	v_pk_fma_f32 v[184:185], v[98:99], v[58:59], v[122:123]
	v_pk_fma_f32 v[186:187], v[100:101], v[60:61], v[124:125]
	v_pk_fma_f32 v[188:189], v[102:103], v[62:63], v[126:127]
	v_pk_fma_f32 v[190:191], v[104:105], v[64:65], v[128:129]
	v_pk_fma_f32 v[176:177], v[74:75], v[2:3], v[176:177]
	v_pk_fma_f32 v[178:179], v[76:77], v[4:5], v[178:179]
	v_pk_fma_f32 v[180:181], v[78:79], v[6:7], v[180:181]
	v_pk_fma_f32 v[182:183], v[80:81], v[8:9], v[182:183]
	v_pk_fma_f32 v[184:185], v[106:107], v[10:11], v[184:185]
	v_pk_fma_f32 v[186:187], v[108:109], v[12:13], v[186:187]
	v_pk_fma_f32 v[188:189], v[110:111], v[14:15], v[188:189]
	v_pk_fma_f32 v[190:191], v[112:113], v[16:17], v[190:191]
	v_pk_fma_f32 v[176:177], v[82:83], v[18:19], v[176:177]
	v_pk_fma_f32 v[178:179], v[84:85], v[20:21], v[178:179]
	v_pk_fma_f32 v[180:181], v[86:87], v[22:23], v[180:181]
	v_pk_fma_f32 v[182:183], v[88:89], v[24:25], v[182:183]
	v_pk_fma_f32 v[184:185], v[114:115], v[26:27], v[184:185]
	v_pk_fma_f32 v[186:187], v[116:117], v[28:29], v[186:187]
	v_pk_fma_f32 v[188:189], v[118:119], v[30:31], v[188:189]
	v_pk_fma_f32 v[190:191], v[120:121], v[32:33], v[190:191]
	v_pk_mul_f32 v[192:193], v[176:177], v[214:215]
	v_pk_mul_f32 v[194:195], v[178:179], v[214:215]
	v_pk_mul_f32 v[196:197], v[180:181], v[214:215]
	v_pk_mul_f32 v[198:199], v[182:183], v[214:215]
	v_exp_f32_e32 v192, v192
	v_exp_f32_e32 v193, v193
	v_exp_f32_e32 v194, v194
	v_exp_f32_e32 v195, v195
	v_exp_f32_e32 v196, v196
	v_exp_f32_e32 v197, v197
	v_exp_f32_e32 v198, v198
	v_exp_f32_e32 v199, v199
	v_pk_add_f32 v[192:193], v[192:193], 1.0 op_sel_hi:[1,0]
	v_pk_add_f32 v[194:195], v[194:195], 1.0 op_sel_hi:[1,0]
	v_pk_add_f32 v[196:197], v[196:197], 1.0 op_sel_hi:[1,0]
	v_pk_add_f32 v[198:199], v[198:199], 1.0 op_sel_hi:[1,0]
	v_rcp_f32_e32 v192, v192
	v_rcp_f32_e32 v193, v193
	v_rcp_f32_e32 v194, v194
	v_rcp_f32_e32 v195, v195
	v_rcp_f32_e32 v196, v196
	v_rcp_f32_e32 v197, v197
	v_rcp_f32_e32 v198, v198
	v_rcp_f32_e32 v199, v199
	s_waitcnt lgkmcnt(0)
	v_lshlrev_b32_e32 v34, 16, v204
	v_and_b32_e32 v35, 0xffff0000, v204
	v_lshlrev_b32_e32 v36, 16, v205
	v_and_b32_e32 v37, 0xffff0000, v205
	v_lshlrev_b32_e32 v38, 16, v206
	v_and_b32_e32 v39, 0xffff0000, v206
	v_lshlrev_b32_e32 v40, 16, v207
	v_and_b32_e32 v41, 0xffff0000, v207
	v_lshlrev_b32_e32 v42, 16, v210
	v_and_b32_e32 v43, 0xffff0000, v210
	v_lshlrev_b32_e32 v44, 16, v211
	v_and_b32_e32 v45, 0xffff0000, v211
	v_lshlrev_b32_e32 v46, 16, v212
	v_and_b32_e32 v47, 0xffff0000, v212
	v_lshlrev_b32_e32 v48, 16, v213
	v_and_b32_e32 v49, 0xffff0000, v213
	ds_read_b128 v[204:207], v222 offset:3168
	ds_read_b128 v[210:213], v222 offset:3296
	v_pk_mul_f32 v[176:177], v[176:177], v[192:193]
	v_pk_mul_f32 v[178:179], v[178:179], v[194:195]
	v_pk_mul_f32 v[180:181], v[180:181], v[196:197]
	v_pk_mul_f32 v[182:183], v[182:183], v[198:199]
	v_pk_mul_f32 v[176:177], v[176:177], v[184:185]
	v_pk_mul_f32 v[178:179], v[178:179], v[186:187]
	v_pk_mul_f32 v[180:181], v[180:181], v[188:189]
	v_pk_mul_f32 v[182:183], v[182:183], v[190:191]
	v_cvt_pk_bf16_f32 v200, v176, v177
	v_cvt_pk_bf16_f32 v201, v178, v179
	v_cvt_pk_bf16_f32 v202, v180, v181
	v_cvt_pk_bf16_f32 v203, v182, v183
	global_store_dwordx4 v223, v[200:203], s[12:13] sc1
	v_add_u32_e32 v223, 0x1600, v223
	v_pk_fma_f32 v[176:177], v[66:67], v[2:3], v[90:91]
	v_pk_fma_f32 v[178:179], v[68:69], v[4:5], v[92:93]
	v_pk_fma_f32 v[180:181], v[70:71], v[6:7], v[94:95]
	v_pk_fma_f32 v[182:183], v[72:73], v[8:9], v[96:97]
	v_pk_fma_f32 v[184:185], v[98:99], v[10:11], v[122:123]
	v_pk_fma_f32 v[186:187], v[100:101], v[12:13], v[124:125]
	v_pk_fma_f32 v[188:189], v[102:103], v[14:15], v[126:127]
	v_pk_fma_f32 v[190:191], v[104:105], v[16:17], v[128:129]
	v_pk_fma_f32 v[176:177], v[74:75], v[18:19], v[176:177]
	v_pk_fma_f32 v[178:179], v[76:77], v[20:21], v[178:179]
	v_pk_fma_f32 v[180:181], v[78:79], v[22:23], v[180:181]
	v_pk_fma_f32 v[182:183], v[80:81], v[24:25], v[182:183]
	v_pk_fma_f32 v[184:185], v[106:107], v[26:27], v[184:185]
	v_pk_fma_f32 v[186:187], v[108:109], v[28:29], v[186:187]
	v_pk_fma_f32 v[188:189], v[110:111], v[30:31], v[188:189]
	v_pk_fma_f32 v[190:191], v[112:113], v[32:33], v[190:191]
	v_pk_fma_f32 v[176:177], v[82:83], v[34:35], v[176:177]
	v_pk_fma_f32 v[178:179], v[84:85], v[36:37], v[178:179]
	v_pk_fma_f32 v[180:181], v[86:87], v[38:39], v[180:181]
	v_pk_fma_f32 v[182:183], v[88:89], v[40:41], v[182:183]
	v_pk_fma_f32 v[184:185], v[114:115], v[42:43], v[184:185]
	v_pk_fma_f32 v[186:187], v[116:117], v[44:45], v[186:187]
	v_pk_fma_f32 v[188:189], v[118:119], v[46:47], v[188:189]
	v_pk_fma_f32 v[190:191], v[120:121], v[48:49], v[190:191]
	v_pk_mul_f32 v[192:193], v[176:177], v[214:215]
	v_pk_mul_f32 v[194:195], v[178:179], v[214:215]
	v_pk_mul_f32 v[196:197], v[180:181], v[214:215]
	v_pk_mul_f32 v[198:199], v[182:183], v[214:215]
	v_exp_f32_e32 v192, v192
	v_exp_f32_e32 v193, v193
	v_exp_f32_e32 v194, v194
	v_exp_f32_e32 v195, v195
	v_exp_f32_e32 v196, v196
	v_exp_f32_e32 v197, v197
	v_exp_f32_e32 v198, v198
	v_exp_f32_e32 v199, v199
	v_pk_add_f32 v[192:193], v[192:193], 1.0 op_sel_hi:[1,0]
	v_pk_add_f32 v[194:195], v[194:195], 1.0 op_sel_hi:[1,0]
	v_pk_add_f32 v[196:197], v[196:197], 1.0 op_sel_hi:[1,0]
	v_pk_add_f32 v[198:199], v[198:199], 1.0 op_sel_hi:[1,0]
	v_rcp_f32_e32 v192, v192
	v_rcp_f32_e32 v193, v193
	v_rcp_f32_e32 v194, v194
	v_rcp_f32_e32 v195, v195
	v_rcp_f32_e32 v196, v196
	v_rcp_f32_e32 v197, v197
	v_rcp_f32_e32 v198, v198
	v_rcp_f32_e32 v199, v199
	s_waitcnt lgkmcnt(0)
	v_lshlrev_b32_e32 v50, 16, v204
	v_and_b32_e32 v51, 0xffff0000, v204
	v_lshlrev_b32_e32 v52, 16, v205
	v_and_b32_e32 v53, 0xffff0000, v205
	v_lshlrev_b32_e32 v54, 16, v206
	v_and_b32_e32 v55, 0xffff0000, v206
	v_lshlrev_b32_e32 v56, 16, v207
	v_and_b32_e32 v57, 0xffff0000, v207
	v_lshlrev_b32_e32 v58, 16, v210
	v_and_b32_e32 v59, 0xffff0000, v210
	v_lshlrev_b32_e32 v60, 16, v211
	v_and_b32_e32 v61, 0xffff0000, v211
	v_lshlrev_b32_e32 v62, 16, v212
	v_and_b32_e32 v63, 0xffff0000, v212
	v_lshlrev_b32_e32 v64, 16, v213
	v_and_b32_e32 v65, 0xffff0000, v213
	ds_read_b128 v[204:207], v222 offset:3696
	ds_read_b128 v[210:213], v222 offset:3824
	v_pk_mul_f32 v[176:177], v[176:177], v[192:193]
	v_pk_mul_f32 v[178:179], v[178:179], v[194:195]
	v_pk_mul_f32 v[180:181], v[180:181], v[196:197]
	v_pk_mul_f32 v[182:183], v[182:183], v[198:199]
	v_pk_mul_f32 v[176:177], v[176:177], v[184:185]
	v_pk_mul_f32 v[178:179], v[178:179], v[186:187]
	v_pk_mul_f32 v[180:181], v[180:181], v[188:189]
	v_pk_mul_f32 v[182:183], v[182:183], v[190:191]
	v_cvt_pk_bf16_f32 v200, v176, v177
	v_cvt_pk_bf16_f32 v201, v178, v179
	v_cvt_pk_bf16_f32 v202, v180, v181
	v_cvt_pk_bf16_f32 v203, v182, v183
	global_store_dwordx4 v223, v[200:203], s[12:13] sc1
	v_add_u32_e32 v223, 0x1600, v223
	v_pk_fma_f32 v[176:177], v[66:67], v[18:19], v[90:91]
	v_pk_fma_f32 v[178:179], v[68:69], v[20:21], v[92:93]
	v_pk_fma_f32 v[180:181], v[70:71], v[22:23], v[94:95]
	v_pk_fma_f32 v[182:183], v[72:73], v[24:25], v[96:97]
	v_pk_fma_f32 v[184:185], v[98:99], v[26:27], v[122:123]
	v_pk_fma_f32 v[186:187], v[100:101], v[28:29], v[124:125]
	v_pk_fma_f32 v[188:189], v[102:103], v[30:31], v[126:127]
	v_pk_fma_f32 v[190:191], v[104:105], v[32:33], v[128:129]
	v_pk_fma_f32 v[176:177], v[74:75], v[34:35], v[176:177]
	v_pk_fma_f32 v[178:179], v[76:77], v[36:37], v[178:179]
	v_pk_fma_f32 v[180:181], v[78:79], v[38:39], v[180:181]
	v_pk_fma_f32 v[182:183], v[80:81], v[40:41], v[182:183]
	v_pk_fma_f32 v[184:185], v[106:107], v[42:43], v[184:185]
	v_pk_fma_f32 v[186:187], v[108:109], v[44:45], v[186:187]
	v_pk_fma_f32 v[188:189], v[110:111], v[46:47], v[188:189]
	v_pk_fma_f32 v[190:191], v[112:113], v[48:49], v[190:191]
	v_pk_fma_f32 v[176:177], v[82:83], v[50:51], v[176:177]
	v_pk_fma_f32 v[178:179], v[84:85], v[52:53], v[178:179]
	v_pk_fma_f32 v[180:181], v[86:87], v[54:55], v[180:181]
	v_pk_fma_f32 v[182:183], v[88:89], v[56:57], v[182:183]
	v_pk_fma_f32 v[184:185], v[114:115], v[58:59], v[184:185]
	v_pk_fma_f32 v[186:187], v[116:117], v[60:61], v[186:187]
	v_pk_fma_f32 v[188:189], v[118:119], v[62:63], v[188:189]
	v_pk_fma_f32 v[190:191], v[120:121], v[64:65], v[190:191]
	v_pk_mul_f32 v[192:193], v[176:177], v[214:215]
	v_pk_mul_f32 v[194:195], v[178:179], v[214:215]
	v_pk_mul_f32 v[196:197], v[180:181], v[214:215]
	v_pk_mul_f32 v[198:199], v[182:183], v[214:215]
	v_exp_f32_e32 v192, v192
	v_exp_f32_e32 v193, v193
	v_exp_f32_e32 v194, v194
	v_exp_f32_e32 v195, v195
	v_exp_f32_e32 v196, v196
	v_exp_f32_e32 v197, v197
	v_exp_f32_e32 v198, v198
	v_exp_f32_e32 v199, v199
	v_pk_add_f32 v[192:193], v[192:193], 1.0 op_sel_hi:[1,0]
	v_pk_add_f32 v[194:195], v[194:195], 1.0 op_sel_hi:[1,0]
	v_pk_add_f32 v[196:197], v[196:197], 1.0 op_sel_hi:[1,0]
	v_pk_add_f32 v[198:199], v[198:199], 1.0 op_sel_hi:[1,0]
	v_rcp_f32_e32 v192, v192
	v_rcp_f32_e32 v193, v193
	v_rcp_f32_e32 v194, v194
	v_rcp_f32_e32 v195, v195
	v_rcp_f32_e32 v196, v196
	v_rcp_f32_e32 v197, v197
	v_rcp_f32_e32 v198, v198
	v_rcp_f32_e32 v199, v199
	s_waitcnt lgkmcnt(0)
	v_lshlrev_b32_e32 v2, 16, v204
	v_and_b32_e32 v3, 0xffff0000, v204
	v_lshlrev_b32_e32 v4, 16, v205
	v_and_b32_e32 v5, 0xffff0000, v205
	v_lshlrev_b32_e32 v6, 16, v206
	v_and_b32_e32 v7, 0xffff0000, v206
	v_lshlrev_b32_e32 v8, 16, v207
	v_and_b32_e32 v9, 0xffff0000, v207
	v_lshlrev_b32_e32 v10, 16, v210
	v_and_b32_e32 v11, 0xffff0000, v210
	v_lshlrev_b32_e32 v12, 16, v211
	v_and_b32_e32 v13, 0xffff0000, v211
	v_lshlrev_b32_e32 v14, 16, v212
	v_and_b32_e32 v15, 0xffff0000, v212
	v_lshlrev_b32_e32 v16, 16, v213
	v_and_b32_e32 v17, 0xffff0000, v213
	v_cmp_ne_u32_e32 vcc, 31, v224
	s_nop 1
	s_and_saveexec_b64 s[38:39], vcc
	ds_read_b128 v[204:207], v222 offset:4224
	ds_read_b128 v[210:213], v222 offset:4352
	s_or_b64 exec, exec, s[38:39]
	v_pk_mul_f32 v[176:177], v[176:177], v[192:193]
	v_pk_mul_f32 v[178:179], v[178:179], v[194:195]
	v_pk_mul_f32 v[180:181], v[180:181], v[196:197]
	v_pk_mul_f32 v[182:183], v[182:183], v[198:199]
	v_pk_mul_f32 v[176:177], v[176:177], v[184:185]
	v_pk_mul_f32 v[178:179], v[178:179], v[186:187]
	v_pk_mul_f32 v[180:181], v[180:181], v[188:189]
	v_pk_mul_f32 v[182:183], v[182:183], v[190:191]
	v_cvt_pk_bf16_f32 v200, v176, v177
	v_cvt_pk_bf16_f32 v201, v178, v179
	v_cvt_pk_bf16_f32 v202, v180, v181
	v_cvt_pk_bf16_f32 v203, v182, v183
	global_store_dwordx4 v223, v[200:203], s[12:13] sc1
	v_add_u32_e32 v223, 0x1600, v223
	v_pk_fma_f32 v[176:177], v[66:67], v[34:35], v[90:91]
	v_pk_fma_f32 v[178:179], v[68:69], v[36:37], v[92:93]
	v_pk_fma_f32 v[180:181], v[70:71], v[38:39], v[94:95]
	v_pk_fma_f32 v[182:183], v[72:73], v[40:41], v[96:97]
	v_pk_fma_f32 v[184:185], v[98:99], v[42:43], v[122:123]
	v_pk_fma_f32 v[186:187], v[100:101], v[44:45], v[124:125]
	v_pk_fma_f32 v[188:189], v[102:103], v[46:47], v[126:127]
	v_pk_fma_f32 v[190:191], v[104:105], v[48:49], v[128:129]
	v_pk_fma_f32 v[176:177], v[74:75], v[50:51], v[176:177]
	v_pk_fma_f32 v[178:179], v[76:77], v[52:53], v[178:179]
	v_pk_fma_f32 v[180:181], v[78:79], v[54:55], v[180:181]
	v_pk_fma_f32 v[182:183], v[80:81], v[56:57], v[182:183]
	v_pk_fma_f32 v[184:185], v[106:107], v[58:59], v[184:185]
	v_pk_fma_f32 v[186:187], v[108:109], v[60:61], v[186:187]
	v_pk_fma_f32 v[188:189], v[110:111], v[62:63], v[188:189]
	v_pk_fma_f32 v[190:191], v[112:113], v[64:65], v[190:191]
	v_pk_fma_f32 v[176:177], v[82:83], v[2:3], v[176:177]
	v_pk_fma_f32 v[178:179], v[84:85], v[4:5], v[178:179]
	v_pk_fma_f32 v[180:181], v[86:87], v[6:7], v[180:181]
	v_pk_fma_f32 v[182:183], v[88:89], v[8:9], v[182:183]
	v_pk_fma_f32 v[184:185], v[114:115], v[10:11], v[184:185]
	v_pk_fma_f32 v[186:187], v[116:117], v[12:13], v[186:187]
	v_pk_fma_f32 v[188:189], v[118:119], v[14:15], v[188:189]
	v_pk_fma_f32 v[190:191], v[120:121], v[16:17], v[190:191]
	v_pk_mul_f32 v[192:193], v[176:177], v[214:215]
	v_pk_mul_f32 v[194:195], v[178:179], v[214:215]
	v_pk_mul_f32 v[196:197], v[180:181], v[214:215]
	v_pk_mul_f32 v[198:199], v[182:183], v[214:215]
	v_exp_f32_e32 v192, v192
	v_exp_f32_e32 v193, v193
	v_exp_f32_e32 v194, v194
	v_exp_f32_e32 v195, v195
	v_exp_f32_e32 v196, v196
	v_exp_f32_e32 v197, v197
	v_exp_f32_e32 v198, v198
	v_exp_f32_e32 v199, v199
	v_pk_add_f32 v[192:193], v[192:193], 1.0 op_sel_hi:[1,0]
	v_pk_add_f32 v[194:195], v[194:195], 1.0 op_sel_hi:[1,0]
	v_pk_add_f32 v[196:197], v[196:197], 1.0 op_sel_hi:[1,0]
	v_pk_add_f32 v[198:199], v[198:199], 1.0 op_sel_hi:[1,0]
	v_rcp_f32_e32 v192, v192
	v_rcp_f32_e32 v193, v193
	v_rcp_f32_e32 v194, v194
	v_rcp_f32_e32 v195, v195
	v_rcp_f32_e32 v196, v196
	v_rcp_f32_e32 v197, v197
	v_rcp_f32_e32 v198, v198
	v_rcp_f32_e32 v199, v199
	s_waitcnt lgkmcnt(0)
	v_lshlrev_b32_e32 v18, 16, v204
	v_and_b32_e32 v19, 0xffff0000, v204
	v_lshlrev_b32_e32 v20, 16, v205
	v_and_b32_e32 v21, 0xffff0000, v205
	v_lshlrev_b32_e32 v22, 16, v206
	v_and_b32_e32 v23, 0xffff0000, v206
	v_lshlrev_b32_e32 v24, 16, v207
	v_and_b32_e32 v25, 0xffff0000, v207
	v_lshlrev_b32_e32 v26, 16, v210
	v_and_b32_e32 v27, 0xffff0000, v210
	v_lshlrev_b32_e32 v28, 16, v211
	v_and_b32_e32 v29, 0xffff0000, v211
	v_lshlrev_b32_e32 v30, 16, v212
	v_and_b32_e32 v31, 0xffff0000, v212
	v_lshlrev_b32_e32 v32, 16, v213
	v_and_b32_e32 v33, 0xffff0000, v213
	v_cmp_eq_u32_e32 vcc, 31, v224
	s_nop 1
	v_cndmask_b32_e64 v18, v18, 0, vcc
	v_cndmask_b32_e64 v19, v19, 0, vcc
	v_cndmask_b32_e64 v20, v20, 0, vcc
	v_cndmask_b32_e64 v21, v21, 0, vcc
	v_cndmask_b32_e64 v22, v22, 0, vcc
	v_cndmask_b32_e64 v23, v23, 0, vcc
	v_cndmask_b32_e64 v24, v24, 0, vcc
	v_cndmask_b32_e64 v25, v25, 0, vcc
	v_cndmask_b32_e64 v26, v26, 0, vcc
	v_cndmask_b32_e64 v27, v27, 0, vcc
	v_cndmask_b32_e64 v28, v28, 0, vcc
	v_cndmask_b32_e64 v29, v29, 0, vcc
	v_cndmask_b32_e64 v30, v30, 0, vcc
	v_cndmask_b32_e64 v31, v31, 0, vcc
	v_cndmask_b32_e64 v32, v32, 0, vcc
	v_cndmask_b32_e64 v33, v33, 0, vcc
	v_pk_mul_f32 v[176:177], v[176:177], v[192:193]
	v_pk_mul_f32 v[178:179], v[178:179], v[194:195]
	v_pk_mul_f32 v[180:181], v[180:181], v[196:197]
	v_pk_mul_f32 v[182:183], v[182:183], v[198:199]
	v_pk_mul_f32 v[176:177], v[176:177], v[184:185]
	v_pk_mul_f32 v[178:179], v[178:179], v[186:187]
	v_pk_mul_f32 v[180:181], v[180:181], v[188:189]
	v_pk_mul_f32 v[182:183], v[182:183], v[190:191]
	v_cvt_pk_bf16_f32 v200, v176, v177
	v_cvt_pk_bf16_f32 v201, v178, v179
	v_cvt_pk_bf16_f32 v202, v180, v181
	v_cvt_pk_bf16_f32 v203, v182, v183
	global_store_dwordx4 v223, v[200:203], s[12:13] sc1
	v_add_u32_e32 v223, 0x1600, v223
	v_pk_fma_f32 v[176:177], v[66:67], v[50:51], v[90:91]
	v_pk_fma_f32 v[178:179], v[68:69], v[52:53], v[92:93]
	v_pk_fma_f32 v[180:181], v[70:71], v[54:55], v[94:95]
	v_pk_fma_f32 v[182:183], v[72:73], v[56:57], v[96:97]
	v_pk_fma_f32 v[184:185], v[98:99], v[58:59], v[122:123]
	v_pk_fma_f32 v[186:187], v[100:101], v[60:61], v[124:125]
	v_pk_fma_f32 v[188:189], v[102:103], v[62:63], v[126:127]
	v_pk_fma_f32 v[190:191], v[104:105], v[64:65], v[128:129]
	v_pk_fma_f32 v[176:177], v[74:75], v[2:3], v[176:177]
	v_pk_fma_f32 v[178:179], v[76:77], v[4:5], v[178:179]
	v_pk_fma_f32 v[180:181], v[78:79], v[6:7], v[180:181]
	v_pk_fma_f32 v[182:183], v[80:81], v[8:9], v[182:183]
	v_pk_fma_f32 v[184:185], v[106:107], v[10:11], v[184:185]
	v_pk_fma_f32 v[186:187], v[108:109], v[12:13], v[186:187]
	v_pk_fma_f32 v[188:189], v[110:111], v[14:15], v[188:189]
	v_pk_fma_f32 v[190:191], v[112:113], v[16:17], v[190:191]
	v_pk_fma_f32 v[176:177], v[82:83], v[18:19], v[176:177]
	v_pk_fma_f32 v[178:179], v[84:85], v[20:21], v[178:179]
	v_pk_fma_f32 v[180:181], v[86:87], v[22:23], v[180:181]
	v_pk_fma_f32 v[182:183], v[88:89], v[24:25], v[182:183]
	v_pk_fma_f32 v[184:185], v[114:115], v[26:27], v[184:185]
	v_pk_fma_f32 v[186:187], v[116:117], v[28:29], v[186:187]
	v_pk_fma_f32 v[188:189], v[118:119], v[30:31], v[188:189]
	v_pk_fma_f32 v[190:191], v[120:121], v[32:33], v[190:191]
	v_pk_mul_f32 v[192:193], v[176:177], v[214:215]
	v_pk_mul_f32 v[194:195], v[178:179], v[214:215]
	v_pk_mul_f32 v[196:197], v[180:181], v[214:215]
	v_pk_mul_f32 v[198:199], v[182:183], v[214:215]
	v_exp_f32_e32 v192, v192
	v_exp_f32_e32 v193, v193
	v_exp_f32_e32 v194, v194
	v_exp_f32_e32 v195, v195
	v_exp_f32_e32 v196, v196
	v_exp_f32_e32 v197, v197
	v_exp_f32_e32 v198, v198
	v_exp_f32_e32 v199, v199
	v_pk_add_f32 v[192:193], v[192:193], 1.0 op_sel_hi:[1,0]
	v_pk_add_f32 v[194:195], v[194:195], 1.0 op_sel_hi:[1,0]
	v_pk_add_f32 v[196:197], v[196:197], 1.0 op_sel_hi:[1,0]
	v_pk_add_f32 v[198:199], v[198:199], 1.0 op_sel_hi:[1,0]
	v_rcp_f32_e32 v192, v192
	v_rcp_f32_e32 v193, v193
	v_rcp_f32_e32 v194, v194
	v_rcp_f32_e32 v195, v195
	v_rcp_f32_e32 v196, v196
	v_rcp_f32_e32 v197, v197
	v_rcp_f32_e32 v198, v198
	v_rcp_f32_e32 v199, v199
	v_pk_mul_f32 v[176:177], v[176:177], v[192:193]
	v_pk_mul_f32 v[178:179], v[178:179], v[194:195]
	v_pk_mul_f32 v[180:181], v[180:181], v[196:197]
	v_pk_mul_f32 v[182:183], v[182:183], v[198:199]
	v_pk_mul_f32 v[176:177], v[176:177], v[184:185]
	v_pk_mul_f32 v[178:179], v[178:179], v[186:187]
	v_pk_mul_f32 v[180:181], v[180:181], v[188:189]
	v_pk_mul_f32 v[182:183], v[182:183], v[190:191]
	v_cvt_pk_bf16_f32 v200, v176, v177
	v_cvt_pk_bf16_f32 v201, v178, v179
	v_cvt_pk_bf16_f32 v202, v180, v181
	v_cvt_pk_bf16_f32 v203, v182, v183
	s_and_b32 s36, s35, 3
	s_cmp_eq_u32 s36, 3
	s_cselect_b64 s[38:39], -1, 0
	s_cmp_lt_i32 s35, 32
	s_cselect_b64 vcc, -1, 0
	s_or_b64 s[38:39], s[38:39], vcc
	v_cmp_ne_u32_e32 vcc, 31, v224
	s_nop 1
	s_or_b64 vcc, vcc, s[38:39]
	s_and_saveexec_b64 s[38:39], vcc
	global_store_dwordx4 v223, v[200:203], s[12:13] sc1
	s_or_b64 exec, exec, s[38:39]
	v_mov_b32_e32 v74, v0
	s_cmp_lt_i32 s35, 32
	s_cselect_b64 s[4:5], -1, 0
	s_mov_b64 s[6:7], exec
